# QG/KV GEMM epilogues: removed the redundant per-row-group s_waitcnt vmcnt(0) (norm weights already landed after group 1) that made every group wait for the previous group's store acks
# baseline (speedup 1.0000x reference)
.LBB0_260:
	s_andn2_b64 vcc, exec, s[42:43]
	v_and_b32_e32 v146, 0x1fdf, v136
	s_cbranch_vccnz .LBB0_262
	v_lshlrev_b32_e32 v132, 4, v146
	v_cndmask_b32_e64 v137, v230, v132, s[0:1]
	v_pk_mul_f32 v[132:133], v[130:131], v[130:131]
	v_pk_mul_f32 v[134:135], v[128:129], v[128:129]
	s_mov_b32 s0, 0x800000
	v_pk_mov_b32 v[138:139], v[134:135], v[132:133] op_sel:[1,0]
	v_mov_b32_e32 v135, v133
	v_pk_add_f32 v[132:133], v[138:139], v[134:135]
	v_pk_mul_f32 v[134:135], v[126:127], v[126:127]
	v_pk_mul_f32 v[138:139], v[124:125], v[124:125]
	v_pk_add_f32 v[132:133], v[132:133], v[132:133] op_sel:[0,1] op_sel_hi:[1,0]
	v_pk_mov_b32 v[140:141], v[138:139], v[134:135] op_sel:[1,0]
	v_mov_b32_e32 v139, v135
	v_pk_add_f32 v[134:135], v[140:141], v[138:139]
	v_mul_f32_e32 v138, v116, v116
	v_mul_f32_e32 v139, v117, v117
	v_pk_add_f32 v[134:135], v[134:135], v[134:135] op_sel:[0,1] op_sel_hi:[1,0]
	v_mov_b32_e32 v133, v138
	v_mov_b32_e32 v135, v139
	v_pk_add_f32 v[132:133], v[132:133], v[134:135]
	v_mul_f32_e32 v134, v121, v121
	v_mul_f32_e32 v138, v123, v123
	v_mul_f32_e32 v140, v118, v118
	v_mul_f32_e32 v141, v119, v119
	v_pk_fma_f32 v[134:135], v[120:121], v[120:121], v[134:135] op_sel_hi:[1,1,0]
	v_pk_fma_f32 v[138:139], v[122:123], v[122:123], v[138:139] op_sel_hi:[1,1,0]
	v_mov_b32_e32 v135, v140
	v_mov_b32_e32 v139, v141
	v_pk_add_f32 v[134:135], v[134:135], v[138:139]
	s_nop 0
	v_pk_add_f32 v[132:133], v[132:133], v[134:135]
	v_and_b32_e32 v134, 64, v229
	v_add_f32_e32 v132, v132, v133
	v_xor_b32_e32 v133, 16, v229
	v_add_u32_e32 v134, 64, v134
	v_cmp_lt_i32_e32 vcc, v133, v134
	s_nop 1
	v_cndmask_b32_e32 v133, v229, v133, vcc
	v_lshlrev_b32_e32 v133, 2, v133
	ds_bpermute_b32 v133, v133, v132
	s_waitcnt lgkmcnt(0)
	v_add_f32_e32 v132, v132, v133
	v_xor_b32_e32 v133, 32, v229
	v_cmp_lt_i32_e32 vcc, v133, v134
	s_nop 1
	v_cndmask_b32_e32 v133, v229, v133, vcc
	v_lshlrev_b32_e32 v133, 2, v133
	ds_bpermute_b32 v134, v133, v132
	s_waitcnt lgkmcnt(0)
	v_add_f32_e32 v132, v132, v134
	v_fmamk_f32 v132, v132, 0x3c800000, v226
	v_cmp_gt_f32_e32 vcc, s0, v132
	v_mul_f32_e32 v134, 0x4b800000, v132
	s_nop 0
	v_cndmask_b32_e32 v132, v132, v134, vcc
	v_rsq_f32_e32 v132, v132
	s_nop 0
	v_mul_f32_e32 v134, 0x45800000, v132
	v_cndmask_b32_e32 v132, v132, v134, vcc
	v_pk_mul_f32 v[128:129], v[128:129], v[132:133] op_sel_hi:[1,0]
	v_pk_mul_f32 v[130:131], v[130:131], v[132:133] op_sel_hi:[1,0]
	v_pk_mul_f32 v[138:139], v[44:45], v[128:129]
	v_lshlrev_b32_e32 v128, 2, v137
	v_mov_b32_e32 v129, v3
	v_pk_mul_f32 v[140:141], v[46:47], v[130:131]
	v_lshl_add_u64 v[128:129], v[164:165], 0, v[128:129]
	v_pk_mul_f32 v[124:125], v[124:125], v[132:133] op_sel_hi:[1,0]
	v_pk_mul_f32 v[126:127], v[126:127], v[132:133] op_sel_hi:[1,0]
	v_pk_mul_f32 v[120:121], v[120:121], v[132:133] op_sel_hi:[1,0]
	v_pk_mul_f32 v[122:123], v[122:123], v[132:133] op_sel_hi:[1,0]
	v_pk_mul_f32 v[116:117], v[116:117], v[132:133] op_sel_hi:[1,0]
	v_pk_mul_f32 v[118:119], v[118:119], v[132:133] op_sel_hi:[1,0]
	ds_bpermute_b32 v144, v133, v138
	ds_bpermute_b32 v145, v133, v139
	ds_bpermute_b32 v142, v133, v140
	ds_bpermute_b32 v143, v133, v141
	global_load_dwordx4 v[132:135], v[128:129], off
	s_nop 0
	global_load_dwordx4 v[128:131], v[128:129], off offset:16
	v_pk_mul_f32 v[126:127], v[42:43], v[126:127]
	v_pk_mul_f32 v[124:125], v[40:41], v[124:125]
	v_pk_mul_f32 v[122:123], v[38:39], v[122:123]
	v_pk_mul_f32 v[120:121], v[36:37], v[120:121]
	v_pk_mul_f32 v[118:119], v[34:35], v[118:119]
	v_pk_mul_f32 v[116:117], v[32:33], v[116:117]
	s_waitcnt vmcnt(1)
	v_mov_b32_e32 v148, v133
	v_mov_b32_e32 v149, v135
	s_waitcnt lgkmcnt(2)
	v_pk_mul_f32 v[144:145], v[148:149], v[144:145]
	s_waitcnt vmcnt(0)
	v_mov_b32_e32 v148, v129
	v_mov_b32_e32 v149, v131
	s_waitcnt lgkmcnt(0)
	v_pk_mul_f32 v[142:143], v[148:149], v[142:143]
	v_xor_b32_e32 v133, 0x80000000, v144
	v_xor_b32_e32 v129, 0x80000000, v142
	v_xor_b32_e32 v131, 0x80000000, v143
	v_xor_b32_e32 v135, 0x80000000, v145
	v_cndmask_b32_e64 v145, v145, v135, s[4:5]
	v_cndmask_b32_e64 v144, v144, v133, s[4:5]
	v_cndmask_b32_e64 v143, v143, v131, s[4:5]
	v_cndmask_b32_e64 v142, v142, v129, s[4:5]
	v_mov_b32_e32 v129, v130
	v_mov_b32_e32 v133, v134
	v_pk_fma_f32 v[130:131], v[128:129], v[140:141], v[142:143]
	v_pk_fma_f32 v[128:129], v[132:133], v[138:139], v[144:145]

.LBB0_283:
	s_andn2_b64 vcc, exec, s[42:43]
	v_and_b32_e32 v130, 0x1fef, v120
	s_cbranch_vccnz .LBB0_285
	v_lshlrev_b32_e32 v116, 4, v130
	v_cndmask_b32_e64 v121, v230, v116, s[0:1]
	v_pk_mul_f32 v[116:117], v[114:115], v[114:115]
	v_pk_mul_f32 v[118:119], v[112:113], v[112:113]
	s_mov_b32 s0, 0x800000
	v_pk_mov_b32 v[122:123], v[118:119], v[116:117] op_sel:[1,0]
	v_mov_b32_e32 v119, v117
	v_pk_add_f32 v[116:117], v[122:123], v[118:119]
	v_pk_mul_f32 v[118:119], v[110:111], v[110:111]
	v_pk_mul_f32 v[122:123], v[108:109], v[108:109]
	v_pk_add_f32 v[116:117], v[116:117], v[116:117] op_sel:[0,1] op_sel_hi:[1,0]
	v_pk_mov_b32 v[124:125], v[122:123], v[118:119] op_sel:[1,0]
	v_mov_b32_e32 v123, v119
	v_pk_add_f32 v[118:119], v[124:125], v[122:123]
	v_mul_f32_e32 v122, v100, v100
	v_mul_f32_e32 v123, v101, v101
	v_pk_add_f32 v[118:119], v[118:119], v[118:119] op_sel:[0,1] op_sel_hi:[1,0]
	v_mov_b32_e32 v117, v122
	v_mov_b32_e32 v119, v123
	v_pk_add_f32 v[116:117], v[116:117], v[118:119]
	v_mul_f32_e32 v118, v105, v105
	v_mul_f32_e32 v122, v107, v107
	v_mul_f32_e32 v124, v102, v102
	v_mul_f32_e32 v125, v103, v103
	v_pk_fma_f32 v[118:119], v[104:105], v[104:105], v[118:119] op_sel_hi:[1,1,0]
	v_pk_fma_f32 v[122:123], v[106:107], v[106:107], v[122:123] op_sel_hi:[1,1,0]
	v_mov_b32_e32 v119, v124
	v_mov_b32_e32 v123, v125
	v_pk_add_f32 v[118:119], v[118:119], v[122:123]
	s_nop 0
	v_pk_add_f32 v[116:117], v[116:117], v[118:119]
	v_and_b32_e32 v118, 64, v229
	v_add_f32_e32 v116, v116, v117
	v_xor_b32_e32 v117, 16, v229
	v_add_u32_e32 v118, 64, v118
	v_cmp_lt_i32_e32 vcc, v117, v118
	s_nop 1
	v_cndmask_b32_e32 v117, v229, v117, vcc
	v_lshlrev_b32_e32 v117, 2, v117
	ds_bpermute_b32 v117, v117, v116
	s_waitcnt lgkmcnt(0)
	v_add_f32_e32 v116, v116, v117
	v_xor_b32_e32 v117, 32, v229
	v_cmp_lt_i32_e32 vcc, v117, v118
	s_nop 1
	v_cndmask_b32_e32 v117, v229, v117, vcc
	v_lshlrev_b32_e32 v117, 2, v117
	ds_bpermute_b32 v118, v117, v116
	s_waitcnt lgkmcnt(0)
	v_add_f32_e32 v116, v116, v118
	v_fmamk_f32 v116, v116, 0x3c800000, v226
	v_cmp_gt_f32_e32 vcc, s0, v116
	v_mul_f32_e32 v118, 0x4b800000, v116
	s_nop 0
	v_cndmask_b32_e32 v116, v116, v118, vcc
	v_rsq_f32_e32 v116, v116
	s_nop 0
	v_mul_f32_e32 v118, 0x45800000, v116
	v_cndmask_b32_e32 v116, v116, v118, vcc
	v_pk_mul_f32 v[112:113], v[112:113], v[116:117] op_sel_hi:[1,0]
	v_pk_mul_f32 v[114:115], v[114:115], v[116:117] op_sel_hi:[1,0]
	v_pk_mul_f32 v[122:123], v[44:45], v[112:113]
	v_lshlrev_b32_e32 v112, 2, v121
	v_mov_b32_e32 v113, v3
	v_pk_mul_f32 v[124:125], v[46:47], v[114:115]
	v_lshl_add_u64 v[112:113], v[164:165], 0, v[112:113]
	v_pk_mul_f32 v[108:109], v[108:109], v[116:117] op_sel_hi:[1,0]
	v_pk_mul_f32 v[110:111], v[110:111], v[116:117] op_sel_hi:[1,0]
	v_pk_mul_f32 v[104:105], v[104:105], v[116:117] op_sel_hi:[1,0]
	v_pk_mul_f32 v[106:107], v[106:107], v[116:117] op_sel_hi:[1,0]
	v_pk_mul_f32 v[100:101], v[100:101], v[116:117] op_sel_hi:[1,0]
	v_pk_mul_f32 v[102:103], v[102:103], v[116:117] op_sel_hi:[1,0]
	ds_bpermute_b32 v128, v117, v122
	ds_bpermute_b32 v129, v117, v123
	ds_bpermute_b32 v126, v117, v124
	ds_bpermute_b32 v127, v117, v125
	global_load_dwordx4 v[116:119], v[112:113], off
	s_nop 0
	global_load_dwordx4 v[112:115], v[112:113], off offset:16
	v_pk_mul_f32 v[110:111], v[42:43], v[110:111]
	v_pk_mul_f32 v[108:109], v[40:41], v[108:109]
	v_pk_mul_f32 v[106:107], v[38:39], v[106:107]
	v_pk_mul_f32 v[104:105], v[36:37], v[104:105]
	v_pk_mul_f32 v[102:103], v[34:35], v[102:103]
	v_pk_mul_f32 v[100:101], v[32:33], v[100:101]
	s_waitcnt vmcnt(1)
	v_mov_b32_e32 v132, v117
	v_mov_b32_e32 v133, v119
	s_waitcnt lgkmcnt(2)
	v_pk_mul_f32 v[128:129], v[132:133], v[128:129]
	s_waitcnt vmcnt(0)
	v_mov_b32_e32 v132, v113
	v_mov_b32_e32 v133, v115
	s_waitcnt lgkmcnt(0)
	v_pk_mul_f32 v[126:127], v[132:133], v[126:127]
	v_xor_b32_e32 v117, 0x80000000, v128
	v_xor_b32_e32 v113, 0x80000000, v126
	v_xor_b32_e32 v115, 0x80000000, v127
	v_xor_b32_e32 v119, 0x80000000, v129
	v_cndmask_b32_e64 v129, v129, v119, s[4:5]
	v_cndmask_b32_e64 v128, v128, v117, s[4:5]
	v_cndmask_b32_e64 v127, v127, v115, s[4:5]
	v_cndmask_b32_e64 v126, v126, v113, s[4:5]
	v_mov_b32_e32 v113, v114
	v_mov_b32_e32 v117, v118
	v_pk_fma_f32 v[114:115], v[112:113], v[124:125], v[126:127]
	v_pk_fma_f32 v[112:113], v[116:117], v[122:123], v[128:129]

.LBB0_306:
	s_andn2_b64 vcc, exec, s[42:43]
	v_and_b32_e32 v114, 0x1fff, v104
	s_cbranch_vccnz .LBB0_308
	v_lshlrev_b32_e32 v100, 4, v114
	v_cndmask_b32_e64 v105, v230, v100, s[0:1]
	v_pk_mul_f32 v[100:101], v[98:99], v[98:99]
	v_pk_mul_f32 v[102:103], v[96:97], v[96:97]
	s_mov_b32 s0, 0x800000
	v_pk_mov_b32 v[106:107], v[102:103], v[100:101] op_sel:[1,0]
	v_mov_b32_e32 v103, v101
	v_pk_add_f32 v[100:101], v[106:107], v[102:103]
	v_pk_mul_f32 v[102:103], v[94:95], v[94:95]
	v_pk_mul_f32 v[106:107], v[92:93], v[92:93]
	v_pk_add_f32 v[100:101], v[100:101], v[100:101] op_sel:[0,1] op_sel_hi:[1,0]
	v_pk_mov_b32 v[108:109], v[106:107], v[102:103] op_sel:[1,0]
	v_mov_b32_e32 v107, v103
	v_pk_add_f32 v[102:103], v[108:109], v[106:107]
	v_mul_f32_e32 v106, v84, v84
	v_mul_f32_e32 v107, v85, v85
	v_pk_add_f32 v[102:103], v[102:103], v[102:103] op_sel:[0,1] op_sel_hi:[1,0]
	v_mov_b32_e32 v101, v106
	v_mov_b32_e32 v103, v107
	v_pk_add_f32 v[100:101], v[100:101], v[102:103]
	v_mul_f32_e32 v102, v89, v89
	v_mul_f32_e32 v106, v91, v91
	v_mul_f32_e32 v108, v86, v86
	v_mul_f32_e32 v109, v87, v87
	v_pk_fma_f32 v[102:103], v[88:89], v[88:89], v[102:103] op_sel_hi:[1,1,0]
	v_pk_fma_f32 v[106:107], v[90:91], v[90:91], v[106:107] op_sel_hi:[1,1,0]
	v_mov_b32_e32 v103, v108
	v_mov_b32_e32 v107, v109
	v_pk_add_f32 v[102:103], v[102:103], v[106:107]
	s_nop 0
	v_pk_add_f32 v[100:101], v[100:101], v[102:103]
	v_and_b32_e32 v102, 64, v229
	v_add_f32_e32 v100, v100, v101
	v_xor_b32_e32 v101, 16, v229
	v_add_u32_e32 v102, 64, v102
	v_cmp_lt_i32_e32 vcc, v101, v102
	s_nop 1
	v_cndmask_b32_e32 v101, v229, v101, vcc
	v_lshlrev_b32_e32 v101, 2, v101
	ds_bpermute_b32 v101, v101, v100
	s_waitcnt lgkmcnt(0)
	v_add_f32_e32 v100, v100, v101
	v_xor_b32_e32 v101, 32, v229
	v_cmp_lt_i32_e32 vcc, v101, v102
	s_nop 1
	v_cndmask_b32_e32 v101, v229, v101, vcc
	v_lshlrev_b32_e32 v101, 2, v101
	ds_bpermute_b32 v102, v101, v100
	s_waitcnt lgkmcnt(0)
	v_add_f32_e32 v100, v100, v102
	v_fmamk_f32 v100, v100, 0x3c800000, v226
	v_cmp_gt_f32_e32 vcc, s0, v100
	v_mul_f32_e32 v102, 0x4b800000, v100
	s_nop 0
	v_cndmask_b32_e32 v100, v100, v102, vcc
	v_rsq_f32_e32 v100, v100
	s_nop 0
	v_mul_f32_e32 v102, 0x45800000, v100
	v_cndmask_b32_e32 v100, v100, v102, vcc
	v_pk_mul_f32 v[96:97], v[96:97], v[100:101] op_sel_hi:[1,0]
	v_pk_mul_f32 v[98:99], v[98:99], v[100:101] op_sel_hi:[1,0]
	v_pk_mul_f32 v[106:107], v[44:45], v[96:97]
	v_lshlrev_b32_e32 v96, 2, v105
	v_mov_b32_e32 v97, v3
	v_pk_mul_f32 v[108:109], v[46:47], v[98:99]
	v_lshl_add_u64 v[96:97], v[164:165], 0, v[96:97]
	v_pk_mul_f32 v[92:93], v[92:93], v[100:101] op_sel_hi:[1,0]
	v_pk_mul_f32 v[94:95], v[94:95], v[100:101] op_sel_hi:[1,0]
	v_pk_mul_f32 v[88:89], v[88:89], v[100:101] op_sel_hi:[1,0]
	v_pk_mul_f32 v[90:91], v[90:91], v[100:101] op_sel_hi:[1,0]
	v_pk_mul_f32 v[84:85], v[84:85], v[100:101] op_sel_hi:[1,0]
	v_pk_mul_f32 v[86:87], v[86:87], v[100:101] op_sel_hi:[1,0]
	ds_bpermute_b32 v112, v101, v106
	ds_bpermute_b32 v113, v101, v107
	ds_bpermute_b32 v110, v101, v108
	ds_bpermute_b32 v111, v101, v109
	global_load_dwordx4 v[100:103], v[96:97], off
	s_nop 0
	global_load_dwordx4 v[96:99], v[96:97], off offset:16
	v_pk_mul_f32 v[94:95], v[42:43], v[94:95]
	v_pk_mul_f32 v[92:93], v[40:41], v[92:93]
	v_pk_mul_f32 v[90:91], v[38:39], v[90:91]
	v_pk_mul_f32 v[88:89], v[36:37], v[88:89]
	v_pk_mul_f32 v[86:87], v[34:35], v[86:87]
	v_pk_mul_f32 v[84:85], v[32:33], v[84:85]
	s_waitcnt vmcnt(1)
	v_mov_b32_e32 v116, v101
	v_mov_b32_e32 v117, v103
	s_waitcnt lgkmcnt(2)
	v_pk_mul_f32 v[112:113], v[116:117], v[112:113]
	s_waitcnt vmcnt(0)
	v_mov_b32_e32 v116, v97
	v_mov_b32_e32 v117, v99
	s_waitcnt lgkmcnt(0)
	v_pk_mul_f32 v[110:111], v[116:117], v[110:111]
	v_xor_b32_e32 v101, 0x80000000, v112
	v_xor_b32_e32 v97, 0x80000000, v110
	v_xor_b32_e32 v99, 0x80000000, v111
	v_xor_b32_e32 v103, 0x80000000, v113
	v_cndmask_b32_e64 v113, v113, v103, s[4:5]
	v_cndmask_b32_e64 v112, v112, v101, s[4:5]
	v_cndmask_b32_e64 v111, v111, v99, s[4:5]
	v_cndmask_b32_e64 v110, v110, v97, s[4:5]
	v_mov_b32_e32 v97, v98
	v_mov_b32_e32 v101, v102
	v_pk_fma_f32 v[98:99], v[96:97], v[108:109], v[110:111]
	v_pk_fma_f32 v[96:97], v[100:101], v[106:107], v[112:113]

.LBB0_329:
	s_andn2_b64 vcc, exec, s[42:43]
	v_and_b32_e32 v98, 0x1fcf, v88
	s_cbranch_vccnz .LBB0_331
	v_lshlrev_b32_e32 v84, 4, v98
	v_cndmask_b32_e64 v89, v230, v84, s[0:1]
	v_pk_mul_f32 v[84:85], v[82:83], v[82:83]
	v_pk_mul_f32 v[86:87], v[80:81], v[80:81]
	s_mov_b32 s0, 0x800000
	v_pk_mov_b32 v[90:91], v[86:87], v[84:85] op_sel:[1,0]
	v_mov_b32_e32 v87, v85
	v_pk_add_f32 v[84:85], v[90:91], v[86:87]
	v_pk_mul_f32 v[86:87], v[78:79], v[78:79]
	v_pk_mul_f32 v[90:91], v[76:77], v[76:77]
	v_pk_add_f32 v[84:85], v[84:85], v[84:85] op_sel:[0,1] op_sel_hi:[1,0]
	v_pk_mov_b32 v[92:93], v[90:91], v[86:87] op_sel:[1,0]
	v_mov_b32_e32 v91, v87
	v_pk_add_f32 v[86:87], v[92:93], v[90:91]
	v_mul_f32_e32 v90, v68, v68
	v_mul_f32_e32 v91, v69, v69
	v_pk_add_f32 v[86:87], v[86:87], v[86:87] op_sel:[0,1] op_sel_hi:[1,0]
	v_mov_b32_e32 v85, v90
	v_mov_b32_e32 v87, v91
	v_pk_add_f32 v[84:85], v[84:85], v[86:87]
	v_mul_f32_e32 v86, v73, v73
	v_mul_f32_e32 v90, v75, v75
	v_mul_f32_e32 v92, v70, v70
	v_mul_f32_e32 v93, v71, v71
	v_pk_fma_f32 v[86:87], v[72:73], v[72:73], v[86:87] op_sel_hi:[1,1,0]
	v_pk_fma_f32 v[90:91], v[74:75], v[74:75], v[90:91] op_sel_hi:[1,1,0]
	v_mov_b32_e32 v87, v92
	v_mov_b32_e32 v91, v93
	v_pk_add_f32 v[86:87], v[86:87], v[90:91]
	s_nop 0
	v_pk_add_f32 v[84:85], v[84:85], v[86:87]
	v_and_b32_e32 v86, 64, v229
	v_add_f32_e32 v84, v84, v85
	v_xor_b32_e32 v85, 16, v229
	v_add_u32_e32 v86, 64, v86
	v_cmp_lt_i32_e32 vcc, v85, v86
	s_nop 1
	v_cndmask_b32_e32 v85, v229, v85, vcc
	v_lshlrev_b32_e32 v85, 2, v85
	ds_bpermute_b32 v85, v85, v84
	s_waitcnt lgkmcnt(0)
	v_add_f32_e32 v84, v84, v85
	v_xor_b32_e32 v85, 32, v229
	v_cmp_lt_i32_e32 vcc, v85, v86
	s_nop 1
	v_cndmask_b32_e32 v85, v229, v85, vcc
	v_lshlrev_b32_e32 v85, 2, v85
	ds_bpermute_b32 v86, v85, v84
	s_waitcnt lgkmcnt(0)
	v_add_f32_e32 v84, v84, v86
	v_fmamk_f32 v84, v84, 0x3c800000, v226
	v_cmp_gt_f32_e32 vcc, s0, v84
	v_mul_f32_e32 v86, 0x4b800000, v84
	s_nop 0
	v_cndmask_b32_e32 v84, v84, v86, vcc
	v_rsq_f32_e32 v84, v84
	s_nop 0
	v_mul_f32_e32 v86, 0x45800000, v84
	v_cndmask_b32_e32 v84, v84, v86, vcc
	v_pk_mul_f32 v[80:81], v[80:81], v[84:85] op_sel_hi:[1,0]
	v_pk_mul_f32 v[82:83], v[82:83], v[84:85] op_sel_hi:[1,0]
	v_pk_mul_f32 v[90:91], v[44:45], v[80:81]
	v_lshlrev_b32_e32 v80, 2, v89
	v_mov_b32_e32 v81, v3
	v_pk_mul_f32 v[92:93], v[46:47], v[82:83]
	v_lshl_add_u64 v[80:81], v[164:165], 0, v[80:81]
	v_pk_mul_f32 v[76:77], v[76:77], v[84:85] op_sel_hi:[1,0]
	v_pk_mul_f32 v[78:79], v[78:79], v[84:85] op_sel_hi:[1,0]
	v_pk_mul_f32 v[72:73], v[72:73], v[84:85] op_sel_hi:[1,0]
	v_pk_mul_f32 v[74:75], v[74:75], v[84:85] op_sel_hi:[1,0]
	v_pk_mul_f32 v[68:69], v[68:69], v[84:85] op_sel_hi:[1,0]
	v_pk_mul_f32 v[70:71], v[70:71], v[84:85] op_sel_hi:[1,0]
	ds_bpermute_b32 v96, v85, v90
	ds_bpermute_b32 v97, v85, v91
	ds_bpermute_b32 v94, v85, v92
	ds_bpermute_b32 v95, v85, v93
	global_load_dwordx4 v[84:87], v[80:81], off
	s_nop 0
	global_load_dwordx4 v[80:83], v[80:81], off offset:16
	v_pk_mul_f32 v[78:79], v[42:43], v[78:79]
	v_pk_mul_f32 v[76:77], v[40:41], v[76:77]
	v_pk_mul_f32 v[74:75], v[38:39], v[74:75]
	v_pk_mul_f32 v[72:73], v[36:37], v[72:73]
	v_pk_mul_f32 v[70:71], v[34:35], v[70:71]
	v_pk_mul_f32 v[68:69], v[32:33], v[68:69]
	s_waitcnt vmcnt(1)
	v_mov_b32_e32 v100, v85
	v_mov_b32_e32 v101, v87
	s_waitcnt lgkmcnt(2)
	v_pk_mul_f32 v[96:97], v[100:101], v[96:97]
	s_waitcnt vmcnt(0)
	v_mov_b32_e32 v100, v81
	v_mov_b32_e32 v101, v83
	s_waitcnt lgkmcnt(0)
	v_pk_mul_f32 v[94:95], v[100:101], v[94:95]
	v_xor_b32_e32 v85, 0x80000000, v96
	v_xor_b32_e32 v81, 0x80000000, v94
	v_xor_b32_e32 v83, 0x80000000, v95
	v_xor_b32_e32 v87, 0x80000000, v97
	v_cndmask_b32_e64 v97, v97, v87, s[4:5]
	v_cndmask_b32_e64 v96, v96, v85, s[4:5]
	v_cndmask_b32_e64 v95, v95, v83, s[4:5]
	v_cndmask_b32_e64 v94, v94, v81, s[4:5]
	v_mov_b32_e32 v81, v82
	v_mov_b32_e32 v85, v86
	v_pk_fma_f32 v[82:83], v[80:81], v[92:93], v[94:95]
	v_pk_fma_f32 v[80:81], v[84:85], v[90:91], v[96:97]

.LBB0_352:
	s_andn2_b64 vcc, exec, s[42:43]
	v_and_b32_e32 v82, 0x1fdf, v72
	s_cbranch_vccnz .LBB0_354
	v_lshlrev_b32_e32 v68, 4, v82
	v_cndmask_b32_e64 v73, v230, v68, s[0:1]
	v_pk_mul_f32 v[68:69], v[66:67], v[66:67]
	v_pk_mul_f32 v[70:71], v[64:65], v[64:65]
	s_mov_b32 s0, 0x800000
	v_pk_mov_b32 v[74:75], v[70:71], v[68:69] op_sel:[1,0]
	v_mov_b32_e32 v71, v69
	v_pk_add_f32 v[68:69], v[74:75], v[70:71]
	v_pk_mul_f32 v[70:71], v[62:63], v[62:63]
	v_pk_mul_f32 v[74:75], v[60:61], v[60:61]
	v_pk_add_f32 v[68:69], v[68:69], v[68:69] op_sel:[0,1] op_sel_hi:[1,0]
	v_pk_mov_b32 v[76:77], v[74:75], v[70:71] op_sel:[1,0]
	v_mov_b32_e32 v75, v71
	v_pk_add_f32 v[70:71], v[76:77], v[74:75]
	v_mul_f32_e32 v74, v52, v52
	v_mul_f32_e32 v75, v53, v53
	v_pk_add_f32 v[70:71], v[70:71], v[70:71] op_sel:[0,1] op_sel_hi:[1,0]
	v_mov_b32_e32 v69, v74
	v_mov_b32_e32 v71, v75
	v_pk_add_f32 v[68:69], v[68:69], v[70:71]
	v_mul_f32_e32 v70, v57, v57
	v_mul_f32_e32 v74, v59, v59
	v_mul_f32_e32 v76, v54, v54
	v_mul_f32_e32 v77, v55, v55
	v_pk_fma_f32 v[70:71], v[56:57], v[56:57], v[70:71] op_sel_hi:[1,1,0]
	v_pk_fma_f32 v[74:75], v[58:59], v[58:59], v[74:75] op_sel_hi:[1,1,0]
	v_mov_b32_e32 v71, v76
	v_mov_b32_e32 v75, v77
	v_pk_add_f32 v[70:71], v[70:71], v[74:75]
	s_nop 0
	v_pk_add_f32 v[68:69], v[68:69], v[70:71]
	v_and_b32_e32 v70, 64, v229
	v_add_f32_e32 v68, v68, v69
	v_xor_b32_e32 v69, 16, v229
	v_add_u32_e32 v70, 64, v70
	v_cmp_lt_i32_e32 vcc, v69, v70
	s_nop 1
	v_cndmask_b32_e32 v69, v229, v69, vcc
	v_lshlrev_b32_e32 v69, 2, v69
	ds_bpermute_b32 v69, v69, v68
	s_waitcnt lgkmcnt(0)
	v_add_f32_e32 v68, v68, v69
	v_xor_b32_e32 v69, 32, v229
	v_cmp_lt_i32_e32 vcc, v69, v70
	s_nop 1
	v_cndmask_b32_e32 v69, v229, v69, vcc
	v_lshlrev_b32_e32 v69, 2, v69
	ds_bpermute_b32 v70, v69, v68
	s_waitcnt lgkmcnt(0)
	v_add_f32_e32 v68, v68, v70
	v_fmamk_f32 v68, v68, 0x3c800000, v226
	v_cmp_gt_f32_e32 vcc, s0, v68
	v_mul_f32_e32 v70, 0x4b800000, v68
	s_nop 0
	v_cndmask_b32_e32 v68, v68, v70, vcc
	v_rsq_f32_e32 v68, v68
	s_nop 0
	v_mul_f32_e32 v70, 0x45800000, v68
	v_cndmask_b32_e32 v68, v68, v70, vcc
	v_pk_mul_f32 v[64:65], v[64:65], v[68:69] op_sel_hi:[1,0]
	v_pk_mul_f32 v[66:67], v[66:67], v[68:69] op_sel_hi:[1,0]
	v_pk_mul_f32 v[74:75], v[44:45], v[64:65]
	v_lshlrev_b32_e32 v64, 2, v73
	v_mov_b32_e32 v65, v3
	v_pk_mul_f32 v[76:77], v[46:47], v[66:67]
	v_lshl_add_u64 v[64:65], v[164:165], 0, v[64:65]
	v_pk_mul_f32 v[60:61], v[60:61], v[68:69] op_sel_hi:[1,0]
	v_pk_mul_f32 v[62:63], v[62:63], v[68:69] op_sel_hi:[1,0]
	v_pk_mul_f32 v[56:57], v[56:57], v[68:69] op_sel_hi:[1,0]
	v_pk_mul_f32 v[58:59], v[58:59], v[68:69] op_sel_hi:[1,0]
	v_pk_mul_f32 v[52:53], v[52:53], v[68:69] op_sel_hi:[1,0]
	v_pk_mul_f32 v[54:55], v[54:55], v[68:69] op_sel_hi:[1,0]
	ds_bpermute_b32 v80, v69, v74
	ds_bpermute_b32 v81, v69, v75
	ds_bpermute_b32 v78, v69, v76
	ds_bpermute_b32 v79, v69, v77
	global_load_dwordx4 v[68:71], v[64:65], off
	s_nop 0
	global_load_dwordx4 v[64:67], v[64:65], off offset:16
	v_pk_mul_f32 v[62:63], v[42:43], v[62:63]
	v_pk_mul_f32 v[60:61], v[40:41], v[60:61]
	v_pk_mul_f32 v[58:59], v[38:39], v[58:59]
	v_pk_mul_f32 v[56:57], v[36:37], v[56:57]
	v_pk_mul_f32 v[54:55], v[34:35], v[54:55]
	v_pk_mul_f32 v[52:53], v[32:33], v[52:53]
	s_waitcnt vmcnt(1)
	v_mov_b32_e32 v84, v69
	v_mov_b32_e32 v85, v71
	s_waitcnt lgkmcnt(2)
	v_pk_mul_f32 v[80:81], v[84:85], v[80:81]
	s_waitcnt vmcnt(0)
	v_mov_b32_e32 v84, v65
	v_mov_b32_e32 v85, v67
	s_waitcnt lgkmcnt(0)
	v_pk_mul_f32 v[78:79], v[84:85], v[78:79]
	v_xor_b32_e32 v69, 0x80000000, v80
	v_xor_b32_e32 v65, 0x80000000, v78
	v_xor_b32_e32 v67, 0x80000000, v79
	v_xor_b32_e32 v71, 0x80000000, v81
	v_cndmask_b32_e64 v81, v81, v71, s[4:5]
	v_cndmask_b32_e64 v80, v80, v69, s[4:5]
	v_cndmask_b32_e64 v79, v79, v67, s[4:5]
	v_cndmask_b32_e64 v78, v78, v65, s[4:5]
	v_mov_b32_e32 v65, v66
	v_mov_b32_e32 v69, v70
	v_pk_fma_f32 v[66:67], v[64:65], v[76:77], v[78:79]
	v_pk_fma_f32 v[64:65], v[68:69], v[74:75], v[80:81]

.LBB0_375:
	s_andn2_b64 vcc, exec, s[42:43]
	v_and_b32_e32 v66, 0x1fef, v56
	s_cbranch_vccnz .LBB0_377
	v_lshlrev_b32_e32 v52, 4, v66
	v_cndmask_b32_e64 v57, v230, v52, s[0:1]
	v_pk_mul_f32 v[52:53], v[50:51], v[50:51]
	v_pk_mul_f32 v[54:55], v[48:49], v[48:49]
	s_mov_b32 s0, 0x800000
	v_pk_mov_b32 v[58:59], v[54:55], v[52:53] op_sel:[1,0]
	v_mov_b32_e32 v55, v53
	v_pk_add_f32 v[52:53], v[58:59], v[54:55]
	v_pk_mul_f32 v[54:55], v[30:31], v[30:31]
	v_pk_mul_f32 v[58:59], v[28:29], v[28:29]
	v_pk_add_f32 v[52:53], v[52:53], v[52:53] op_sel:[0,1] op_sel_hi:[1,0]
	v_pk_mov_b32 v[60:61], v[58:59], v[54:55] op_sel:[1,0]
	v_mov_b32_e32 v59, v55
	v_pk_add_f32 v[54:55], v[60:61], v[58:59]
	v_mul_f32_e32 v58, v20, v20
	v_mul_f32_e32 v59, v21, v21
	v_pk_add_f32 v[54:55], v[54:55], v[54:55] op_sel:[0,1] op_sel_hi:[1,0]
	v_mov_b32_e32 v53, v58
	v_mov_b32_e32 v55, v59
	v_pk_add_f32 v[52:53], v[52:53], v[54:55]
	v_mul_f32_e32 v54, v25, v25
	v_mul_f32_e32 v58, v27, v27
	v_mul_f32_e32 v60, v22, v22
	v_mul_f32_e32 v61, v23, v23
	v_pk_fma_f32 v[54:55], v[24:25], v[24:25], v[54:55] op_sel_hi:[1,1,0]
	v_pk_fma_f32 v[58:59], v[26:27], v[26:27], v[58:59] op_sel_hi:[1,1,0]
	v_mov_b32_e32 v55, v60
	v_mov_b32_e32 v59, v61
	v_pk_add_f32 v[54:55], v[54:55], v[58:59]
	s_nop 0
	v_pk_add_f32 v[52:53], v[52:53], v[54:55]
	v_and_b32_e32 v54, 64, v229
	v_add_f32_e32 v52, v52, v53
	v_xor_b32_e32 v53, 16, v229
	v_add_u32_e32 v54, 64, v54
	v_cmp_lt_i32_e32 vcc, v53, v54
	s_nop 1
	v_cndmask_b32_e32 v53, v229, v53, vcc
	v_lshlrev_b32_e32 v53, 2, v53
	ds_bpermute_b32 v53, v53, v52
	s_waitcnt lgkmcnt(0)
	v_add_f32_e32 v52, v52, v53
	v_xor_b32_e32 v53, 32, v229
	v_cmp_lt_i32_e32 vcc, v53, v54
	s_nop 1
	v_cndmask_b32_e32 v53, v229, v53, vcc
	v_lshlrev_b32_e32 v53, 2, v53
	ds_bpermute_b32 v54, v53, v52
	s_waitcnt lgkmcnt(0)
	v_add_f32_e32 v52, v52, v54
	v_fmamk_f32 v52, v52, 0x3c800000, v226
	v_cmp_gt_f32_e32 vcc, s0, v52
	v_mul_f32_e32 v54, 0x4b800000, v52
	s_nop 0
	v_cndmask_b32_e32 v52, v52, v54, vcc
	v_rsq_f32_e32 v52, v52
	s_nop 0
	v_mul_f32_e32 v54, 0x45800000, v52
	v_cndmask_b32_e32 v52, v52, v54, vcc
	v_pk_mul_f32 v[48:49], v[48:49], v[52:53] op_sel_hi:[1,0]
	v_pk_mul_f32 v[50:51], v[50:51], v[52:53] op_sel_hi:[1,0]
	v_pk_mul_f32 v[58:59], v[44:45], v[48:49]
	v_lshlrev_b32_e32 v48, 2, v57
	v_mov_b32_e32 v49, v3
	v_pk_mul_f32 v[60:61], v[46:47], v[50:51]
	v_lshl_add_u64 v[48:49], v[164:165], 0, v[48:49]
	v_pk_mul_f32 v[28:29], v[28:29], v[52:53] op_sel_hi:[1,0]
	v_pk_mul_f32 v[30:31], v[30:31], v[52:53] op_sel_hi:[1,0]
	v_pk_mul_f32 v[24:25], v[24:25], v[52:53] op_sel_hi:[1,0]
	v_pk_mul_f32 v[26:27], v[26:27], v[52:53] op_sel_hi:[1,0]
	v_pk_mul_f32 v[20:21], v[20:21], v[52:53] op_sel_hi:[1,0]
	v_pk_mul_f32 v[22:23], v[22:23], v[52:53] op_sel_hi:[1,0]
	ds_bpermute_b32 v64, v53, v58
	ds_bpermute_b32 v65, v53, v59
	ds_bpermute_b32 v62, v53, v60
	ds_bpermute_b32 v63, v53, v61
	global_load_dwordx4 v[52:55], v[48:49], off
	s_nop 0
	global_load_dwordx4 v[48:51], v[48:49], off offset:16
	v_pk_mul_f32 v[30:31], v[42:43], v[30:31]
	v_pk_mul_f32 v[28:29], v[40:41], v[28:29]
	v_pk_mul_f32 v[26:27], v[38:39], v[26:27]
	v_pk_mul_f32 v[24:25], v[36:37], v[24:25]
	v_pk_mul_f32 v[22:23], v[34:35], v[22:23]
	v_pk_mul_f32 v[20:21], v[32:33], v[20:21]
	s_waitcnt vmcnt(1)
	v_mov_b32_e32 v68, v53
	v_mov_b32_e32 v69, v55
	s_waitcnt lgkmcnt(2)
	v_pk_mul_f32 v[64:65], v[68:69], v[64:65]
	s_waitcnt vmcnt(0)
	v_mov_b32_e32 v68, v49
	v_mov_b32_e32 v69, v51
	s_waitcnt lgkmcnt(0)
	v_pk_mul_f32 v[62:63], v[68:69], v[62:63]
	v_xor_b32_e32 v53, 0x80000000, v64
	v_xor_b32_e32 v49, 0x80000000, v62
	v_xor_b32_e32 v51, 0x80000000, v63
	v_xor_b32_e32 v55, 0x80000000, v65
	v_cndmask_b32_e64 v65, v65, v55, s[4:5]
	v_cndmask_b32_e64 v64, v64, v53, s[4:5]
	v_cndmask_b32_e64 v63, v63, v51, s[4:5]
	v_cndmask_b32_e64 v62, v62, v49, s[4:5]
	v_mov_b32_e32 v49, v50
	v_mov_b32_e32 v53, v54
	v_pk_fma_f32 v[50:51], v[48:49], v[60:61], v[62:63]
	v_pk_fma_f32 v[48:49], v[52:53], v[58:59], v[64:65]

.LBB0_398:
	s_andn2_b64 vcc, exec, s[42:43]
	v_and_b32_e32 v48, 0x1fff, v24
	s_cbranch_vccnz .LBB0_400
	v_lshlrev_b32_e32 v20, 4, v48
	v_cndmask_b32_e64 v25, v230, v20, s[0:1]
	v_pk_mul_f32 v[20:21], v[18:19], v[18:19]
	v_pk_mul_f32 v[22:23], v[16:17], v[16:17]
	s_mov_b32 s0, 0x800000
	v_pk_mov_b32 v[26:27], v[22:23], v[20:21] op_sel:[1,0]
	v_mov_b32_e32 v23, v21
	v_pk_add_f32 v[20:21], v[26:27], v[22:23]
	v_pk_mul_f32 v[22:23], v[14:15], v[14:15]
	v_pk_mul_f32 v[26:27], v[12:13], v[12:13]
	v_pk_add_f32 v[20:21], v[20:21], v[20:21] op_sel:[0,1] op_sel_hi:[1,0]
	v_pk_mov_b32 v[28:29], v[26:27], v[22:23] op_sel:[1,0]
	v_mov_b32_e32 v27, v23
	v_pk_add_f32 v[22:23], v[28:29], v[26:27]
	v_mul_f32_e32 v26, v4, v4
	v_mul_f32_e32 v27, v5, v5
	v_pk_add_f32 v[22:23], v[22:23], v[22:23] op_sel:[0,1] op_sel_hi:[1,0]
	v_mov_b32_e32 v21, v26
	v_mov_b32_e32 v23, v27
	v_pk_add_f32 v[20:21], v[20:21], v[22:23]
	v_mul_f32_e32 v22, v9, v9
	v_mul_f32_e32 v26, v11, v11
	v_mul_f32_e32 v28, v6, v6
	v_mul_f32_e32 v29, v7, v7
	v_pk_fma_f32 v[22:23], v[8:9], v[8:9], v[22:23] op_sel_hi:[1,1,0]
	v_pk_fma_f32 v[26:27], v[10:11], v[10:11], v[26:27] op_sel_hi:[1,1,0]
	v_mov_b32_e32 v23, v28
	v_mov_b32_e32 v27, v29
	v_pk_add_f32 v[22:23], v[22:23], v[26:27]
	s_nop 0
	v_pk_add_f32 v[20:21], v[20:21], v[22:23]
	v_and_b32_e32 v22, 64, v229
	v_add_f32_e32 v20, v20, v21
	v_xor_b32_e32 v21, 16, v229
	v_add_u32_e32 v22, 64, v22
	v_cmp_lt_i32_e32 vcc, v21, v22
	s_nop 1
	v_cndmask_b32_e32 v21, v229, v21, vcc
	v_lshlrev_b32_e32 v21, 2, v21
	ds_bpermute_b32 v21, v21, v20
	s_waitcnt lgkmcnt(0)
	v_add_f32_e32 v20, v20, v21
	v_xor_b32_e32 v21, 32, v229
	v_cmp_lt_i32_e32 vcc, v21, v22
	s_nop 1
	v_cndmask_b32_e32 v21, v229, v21, vcc
	v_lshlrev_b32_e32 v21, 2, v21
	ds_bpermute_b32 v22, v21, v20
	s_waitcnt lgkmcnt(0)
	v_add_f32_e32 v20, v20, v22
	v_fmamk_f32 v20, v20, 0x3c800000, v226
	v_cmp_gt_f32_e32 vcc, s0, v20
	v_mul_f32_e32 v22, 0x4b800000, v20
	s_nop 0
	v_cndmask_b32_e32 v20, v20, v22, vcc
	v_rsq_f32_e32 v20, v20
	s_nop 0
	v_mul_f32_e32 v22, 0x45800000, v20
	v_cndmask_b32_e32 v20, v20, v22, vcc
	v_pk_mul_f32 v[16:17], v[16:17], v[20:21] op_sel_hi:[1,0]
	v_pk_mul_f32 v[18:19], v[18:19], v[20:21] op_sel_hi:[1,0]
	v_pk_mul_f32 v[26:27], v[44:45], v[16:17]
	v_lshlrev_b32_e32 v16, 2, v25
	v_mov_b32_e32 v17, v3
	v_pk_mul_f32 v[28:29], v[46:47], v[18:19]
	v_pk_mul_f32 v[4:5], v[4:5], v[20:21] op_sel_hi:[1,0]
	v_lshl_add_u64 v[16:17], v[164:165], 0, v[16:17]
	v_pk_mul_f32 v[12:13], v[12:13], v[20:21] op_sel_hi:[1,0]
	v_pk_mul_f32 v[14:15], v[14:15], v[20:21] op_sel_hi:[1,0]
	v_pk_mul_f32 v[8:9], v[8:9], v[20:21] op_sel_hi:[1,0]
	v_pk_mul_f32 v[10:11], v[10:11], v[20:21] op_sel_hi:[1,0]
	v_pk_mul_f32 v[6:7], v[6:7], v[20:21] op_sel_hi:[1,0]
	v_pk_mul_f32 v[4:5], v[32:33], v[4:5]
	ds_bpermute_b32 v32, v21, v26
	ds_bpermute_b32 v33, v21, v27
	ds_bpermute_b32 v30, v21, v28
	ds_bpermute_b32 v31, v21, v29
	global_load_dwordx4 v[20:23], v[16:17], off
	s_nop 0
	global_load_dwordx4 v[16:19], v[16:17], off offset:16
	v_pk_mul_f32 v[6:7], v[34:35], v[6:7]
	v_pk_mul_f32 v[14:15], v[42:43], v[14:15]
	v_pk_mul_f32 v[12:13], v[40:41], v[12:13]
	v_pk_mul_f32 v[10:11], v[38:39], v[10:11]
	v_pk_mul_f32 v[8:9], v[36:37], v[8:9]
	s_waitcnt vmcnt(1)
	v_mov_b32_e32 v34, v21
	v_mov_b32_e32 v35, v23
	s_waitcnt lgkmcnt(2)
	v_pk_mul_f32 v[32:33], v[34:35], v[32:33]
	s_waitcnt vmcnt(0)
	v_mov_b32_e32 v34, v17
	v_mov_b32_e32 v35, v19
	s_waitcnt lgkmcnt(0)
	v_pk_mul_f32 v[30:31], v[34:35], v[30:31]
	v_xor_b32_e32 v21, 0x80000000, v32
	v_xor_b32_e32 v17, 0x80000000, v30
	v_xor_b32_e32 v19, 0x80000000, v31
	v_xor_b32_e32 v23, 0x80000000, v33
	v_cndmask_b32_e64 v33, v33, v23, s[4:5]
	v_cndmask_b32_e64 v32, v32, v21, s[4:5]
	v_cndmask_b32_e64 v31, v31, v19, s[4:5]
	v_cndmask_b32_e64 v30, v30, v17, s[4:5]
	v_mov_b32_e32 v17, v18
	v_mov_b32_e32 v21, v22
	v_pk_fma_f32 v[18:19], v[16:17], v[28:29], v[30:31]
	v_pk_fma_f32 v[16:17], v[20:21], v[26:27], v[32:33]

.LBB0_456:
	s_andn2_b64 vcc, exec, s[30:31]
	s_cbranch_vccnz .LBB0_458
	v_pk_mul_f32 v[134:135], v[130:131], v[130:131]
	v_pk_mul_f32 v[136:137], v[128:129], v[128:129]
	s_movk_i32 s11, 0x4000
	v_pk_mov_b32 v[138:139], v[136:137], v[134:135] op_sel:[1,0]
	v_mov_b32_e32 v137, v135
	v_pk_add_f32 v[134:135], v[138:139], v[136:137]
	v_pk_mul_f32 v[136:137], v[126:127], v[126:127]
	v_pk_mul_f32 v[138:139], v[124:125], v[124:125]
	v_lshlrev_b32_e32 v2, 4, v132
	v_pk_mov_b32 v[140:141], v[138:139], v[136:137] op_sel:[1,0]
	v_mov_b32_e32 v139, v137
	v_cmp_gt_i32_e32 vcc, s11, v132
	v_and_b32_e32 v2, 0x1fdf0, v2
	v_pk_add_f32 v[136:137], v[140:141], v[138:139]
	v_cndmask_b32_e32 v133, v230, v2, vcc
	v_mul_f32_e32 v2, v116, v116
	v_mul_f32_e32 v138, v117, v117
	v_pk_add_f32 v[134:135], v[134:135], v[134:135] op_sel:[0,1] op_sel_hi:[1,0]
	v_pk_add_f32 v[136:137], v[136:137], v[136:137] op_sel:[0,1] op_sel_hi:[1,0]
	v_mov_b32_e32 v135, v2
	v_mov_b32_e32 v137, v138
	v_mul_f32_e32 v2, v121, v121
	v_mul_f32_e32 v139, v118, v118
	v_pk_add_f32 v[134:135], v[134:135], v[136:137]
	v_pk_fma_f32 v[136:137], v[120:121], v[120:121], v[2:3] op_sel_hi:[1,1,0]
	v_mul_f32_e32 v2, v123, v123
	v_mul_f32_e32 v140, v119, v119
	v_mov_b32_e32 v137, v139
	v_pk_fma_f32 v[138:139], v[122:123], v[122:123], v[2:3] op_sel_hi:[1,1,0]
	s_mov_b32 s11, 0x800000
	v_mov_b32_e32 v139, v140
	v_pk_add_f32 v[136:137], v[136:137], v[138:139]
	s_mov_b32 s30, 0x3e38aa3b
	v_pk_add_f32 v[134:135], v[134:135], v[136:137]
	s_nop 0
	v_add_f32_e32 v2, v134, v135
	v_and_b32_e32 v135, 64, v229
	v_xor_b32_e32 v134, 16, v229
	v_add_u32_e32 v135, 64, v135
	v_cmp_lt_i32_e32 vcc, v134, v135
	s_nop 1
	v_cndmask_b32_e32 v134, v229, v134, vcc
	v_lshlrev_b32_e32 v134, 2, v134
	ds_bpermute_b32 v134, v134, v2
	s_waitcnt lgkmcnt(0)
	v_add_f32_e32 v2, v2, v134
	v_xor_b32_e32 v134, 32, v229
	v_cmp_lt_i32_e32 vcc, v134, v135
	s_nop 1
	v_cndmask_b32_e32 v134, v229, v134, vcc
	v_lshlrev_b32_e32 v145, 2, v134
	ds_bpermute_b32 v134, v145, v2
	s_waitcnt lgkmcnt(0)
	v_add_f32_e32 v2, v2, v134
	v_fmamk_f32 v2, v2, 0x3c800000, v226
	v_cmp_gt_f32_e32 vcc, s11, v2
	v_mul_f32_e32 v134, 0x4b800000, v2
	s_nop 0
	v_cndmask_b32_e32 v2, v2, v134, vcc
	v_rsq_f32_e32 v2, v2
	s_nop 0
	v_mul_f32_e32 v134, 0x45800000, v2
	v_cndmask_b32_e32 v2, v2, v134, vcc
	v_pk_mul_f32 v[128:129], v[128:129], v[2:3] op_sel_hi:[1,0]
	v_pk_mul_f32 v[130:131], v[130:131], v[2:3] op_sel_hi:[1,0]
	v_pk_mul_f32 v[126:127], v[126:127], v[2:3] op_sel_hi:[1,0]
	v_pk_mul_f32 v[124:125], v[124:125], v[2:3] op_sel_hi:[1,0]
	v_pk_mul_f32 v[122:123], v[122:123], v[2:3] op_sel_hi:[1,0]
	v_pk_mul_f32 v[120:121], v[120:121], v[2:3] op_sel_hi:[1,0]
	v_pk_mul_f32 v[118:119], v[118:119], v[2:3] op_sel_hi:[1,0]
	v_pk_mul_f32 v[116:117], v[116:117], v[2:3] op_sel_hi:[1,0]
	v_lshlrev_b32_e32 v2, 2, v133
	v_pk_mul_f32 v[140:141], v[32:33], v[128:129]
	v_pk_mul_f32 v[128:129], v[24:25], v[120:121]
	v_lshl_add_u64 v[120:121], v[154:155], 0, v[2:3]
	v_pk_mul_f32 v[138:139], v[34:35], v[130:131]
	v_pk_mul_f32 v[134:135], v[28:29], v[124:125]
	v_pk_mul_f32 v[136:137], v[30:31], v[126:127]
	v_pk_mul_f32 v[130:131], v[26:27], v[122:123]
	v_pk_mul_f32 v[124:125], v[20:21], v[116:117]
	v_pk_mul_f32 v[126:127], v[22:23], v[118:119]
	global_load_dwordx4 v[116:119], v[120:121], off offset:16
	s_nop 0
	global_load_dwordx4 v[120:123], v[120:121], off
	ds_bpermute_b32 v142, v145, v140
	ds_bpermute_b32 v143, v145, v141
	ds_bpermute_b32 v144, v145, v138
	ds_bpermute_b32 v145, v145, v139
	v_ashrrev_i32_e32 v133, 31, v132
	s_waitcnt vmcnt(1)
	v_mov_b32_e32 v146, v117
	v_mov_b32_e32 v147, v119
	s_waitcnt lgkmcnt(0)
	v_pk_mul_f32 v[144:145], v[146:147], v[144:145]
	s_waitcnt vmcnt(0)
	v_mov_b32_e32 v146, v121
	v_mov_b32_e32 v147, v123
	v_pk_mul_f32 v[142:143], v[146:147], v[142:143]
	v_xor_b32_e32 v119, 0x80000000, v144
	v_xor_b32_e32 v2, 0x80000000, v142
	v_xor_b32_e32 v117, 0x80000000, v143
	v_xor_b32_e32 v121, 0x80000000, v145
	v_cndmask_b32_e64 v145, v145, v121, s[4:5]
	v_cndmask_b32_e64 v144, v144, v119, s[4:5]
	v_cndmask_b32_e64 v143, v143, v117, s[4:5]
	v_cndmask_b32_e64 v142, v142, v2, s[4:5]
	v_mov_b32_e32 v121, v122
	v_mov_b32_e32 v117, v118
	v_lshlrev_b64 v[118:119], 11, v[132:133]
	v_pk_fma_f32 v[120:121], v[120:121], v[140:141], v[142:143]
	v_lshl_add_u64 v[118:119], s[8:9], 0, v[118:119]
	v_pk_fma_f32 v[116:117], v[116:117], v[138:139], v[144:145]
	v_lshl_add_u64 v[118:119], s[24:25], 1, v[118:119]
	v_lshlrev_b32_e32 v2, 1, v152
	v_pk_mul_f32 v[120:121], v[120:121], s[30:31] op_sel_hi:[1,0]
	v_lshl_add_u64 v[118:119], v[118:119], 0, v[2:3]
	v_pk_mul_f32 v[116:117], v[116:117], s[30:31] op_sel_hi:[1,0]
	v_cvt_pk_bf16_f32 v120, v120, v121
	s_nop 0
	v_cvt_pk_bf16_f32 v121, v116, v117
	global_store_dwordx2 v[118:119], v[120:121], off
	v_pk_mul_f32 v[120:121], v[134:135], s[30:31] op_sel_hi:[1,0]
	v_pk_mul_f32 v[116:117], v[136:137], s[30:31] op_sel_hi:[1,0]
	v_cvt_pk_bf16_f32 v120, v120, v121
	s_nop 0
	v_cvt_pk_bf16_f32 v121, v116, v117
	global_store_dwordx2 v[118:119], v[120:121], off offset:32
	v_pk_mul_f32 v[120:121], v[128:129], s[30:31] op_sel_hi:[1,0]
	v_pk_mul_f32 v[116:117], v[130:131], s[30:31] op_sel_hi:[1,0]
	v_cvt_pk_bf16_f32 v120, v120, v121
	s_nop 0
	v_cvt_pk_bf16_f32 v121, v116, v117
	global_store_dwordx2 v[118:119], v[120:121], off offset:64
	v_pk_mul_f32 v[120:121], v[124:125], s[30:31] op_sel_hi:[1,0]
	v_pk_mul_f32 v[116:117], v[126:127], s[30:31] op_sel_hi:[1,0]
	v_cvt_pk_bf16_f32 v120, v120, v121
	s_nop 0
	v_cvt_pk_bf16_f32 v121, v116, v117
	global_store_dwordx2 v[118:119], v[120:121], off offset:96

.LBB0_464:
	s_andn2_b64 vcc, exec, s[30:31]
	s_cbranch_vccnz .LBB0_466
	v_pk_mul_f32 v[118:119], v[114:115], v[114:115]
	v_pk_mul_f32 v[120:121], v[112:113], v[112:113]
	s_movk_i32 s11, 0x4000
	v_pk_mov_b32 v[122:123], v[120:121], v[118:119] op_sel:[1,0]
	v_mov_b32_e32 v121, v119
	v_pk_add_f32 v[118:119], v[122:123], v[120:121]
	v_pk_mul_f32 v[120:121], v[110:111], v[110:111]
	v_pk_mul_f32 v[122:123], v[108:109], v[108:109]
	v_lshlrev_b32_e32 v2, 4, v116
	v_pk_mov_b32 v[124:125], v[122:123], v[120:121] op_sel:[1,0]
	v_mov_b32_e32 v123, v121
	v_cmp_gt_i32_e32 vcc, s11, v116
	v_and_b32_e32 v2, 0x1fef0, v2
	v_pk_add_f32 v[120:121], v[124:125], v[122:123]
	v_cndmask_b32_e32 v117, v230, v2, vcc
	v_mul_f32_e32 v2, v100, v100
	v_mul_f32_e32 v122, v101, v101
	v_pk_add_f32 v[118:119], v[118:119], v[118:119] op_sel:[0,1] op_sel_hi:[1,0]
	v_pk_add_f32 v[120:121], v[120:121], v[120:121] op_sel:[0,1] op_sel_hi:[1,0]
	v_mov_b32_e32 v119, v2
	v_mov_b32_e32 v121, v122
	v_mul_f32_e32 v2, v105, v105
	v_mul_f32_e32 v123, v102, v102
	v_pk_add_f32 v[118:119], v[118:119], v[120:121]
	v_pk_fma_f32 v[120:121], v[104:105], v[104:105], v[2:3] op_sel_hi:[1,1,0]
	v_mul_f32_e32 v2, v107, v107
	v_mul_f32_e32 v124, v103, v103
	v_mov_b32_e32 v121, v123
	v_pk_fma_f32 v[122:123], v[106:107], v[106:107], v[2:3] op_sel_hi:[1,1,0]
	s_mov_b32 s11, 0x800000
	v_mov_b32_e32 v123, v124
	v_pk_add_f32 v[120:121], v[120:121], v[122:123]
	s_mov_b32 s30, 0x3e38aa3b
	v_pk_add_f32 v[118:119], v[118:119], v[120:121]
	s_nop 0
	v_add_f32_e32 v2, v118, v119
	v_and_b32_e32 v119, 64, v229
	v_xor_b32_e32 v118, 16, v229
	v_add_u32_e32 v119, 64, v119
	v_cmp_lt_i32_e32 vcc, v118, v119
	s_nop 1
	v_cndmask_b32_e32 v118, v229, v118, vcc
	v_lshlrev_b32_e32 v118, 2, v118
	ds_bpermute_b32 v118, v118, v2
	s_waitcnt lgkmcnt(0)
	v_add_f32_e32 v2, v2, v118
	v_xor_b32_e32 v118, 32, v229
	v_cmp_lt_i32_e32 vcc, v118, v119
	s_nop 1
	v_cndmask_b32_e32 v118, v229, v118, vcc
	v_lshlrev_b32_e32 v129, 2, v118
	ds_bpermute_b32 v118, v129, v2
	s_waitcnt lgkmcnt(0)
	v_add_f32_e32 v2, v2, v118
	v_fmamk_f32 v2, v2, 0x3c800000, v226
	v_cmp_gt_f32_e32 vcc, s11, v2
	v_mul_f32_e32 v118, 0x4b800000, v2
	s_nop 0
	v_cndmask_b32_e32 v2, v2, v118, vcc
	v_rsq_f32_e32 v2, v2
	s_nop 0
	v_mul_f32_e32 v118, 0x45800000, v2
	v_cndmask_b32_e32 v2, v2, v118, vcc
	v_pk_mul_f32 v[112:113], v[112:113], v[2:3] op_sel_hi:[1,0]
	v_pk_mul_f32 v[114:115], v[114:115], v[2:3] op_sel_hi:[1,0]
	v_pk_mul_f32 v[110:111], v[110:111], v[2:3] op_sel_hi:[1,0]
	v_pk_mul_f32 v[108:109], v[108:109], v[2:3] op_sel_hi:[1,0]
	v_pk_mul_f32 v[106:107], v[106:107], v[2:3] op_sel_hi:[1,0]
	v_pk_mul_f32 v[104:105], v[104:105], v[2:3] op_sel_hi:[1,0]
	v_pk_mul_f32 v[102:103], v[102:103], v[2:3] op_sel_hi:[1,0]
	v_pk_mul_f32 v[100:101], v[100:101], v[2:3] op_sel_hi:[1,0]
	v_lshlrev_b32_e32 v2, 2, v117
	v_pk_mul_f32 v[124:125], v[32:33], v[112:113]
	v_pk_mul_f32 v[112:113], v[24:25], v[104:105]
	v_lshl_add_u64 v[104:105], v[154:155], 0, v[2:3]
	v_pk_mul_f32 v[122:123], v[34:35], v[114:115]
	v_pk_mul_f32 v[118:119], v[28:29], v[108:109]
	v_pk_mul_f32 v[120:121], v[30:31], v[110:111]
	v_pk_mul_f32 v[114:115], v[26:27], v[106:107]
	v_pk_mul_f32 v[108:109], v[20:21], v[100:101]
	v_pk_mul_f32 v[110:111], v[22:23], v[102:103]
	global_load_dwordx4 v[100:103], v[104:105], off offset:16
	s_nop 0
	global_load_dwordx4 v[104:107], v[104:105], off
	ds_bpermute_b32 v126, v129, v124
	ds_bpermute_b32 v127, v129, v125
	ds_bpermute_b32 v128, v129, v122
	ds_bpermute_b32 v129, v129, v123
	v_ashrrev_i32_e32 v117, 31, v116
	s_waitcnt vmcnt(1)
	v_mov_b32_e32 v130, v101
	v_mov_b32_e32 v131, v103
	s_waitcnt lgkmcnt(0)
	v_pk_mul_f32 v[128:129], v[130:131], v[128:129]
	s_waitcnt vmcnt(0)
	v_mov_b32_e32 v130, v105
	v_mov_b32_e32 v131, v107
	v_pk_mul_f32 v[126:127], v[130:131], v[126:127]
	v_xor_b32_e32 v103, 0x80000000, v128
	v_xor_b32_e32 v2, 0x80000000, v126
	v_xor_b32_e32 v101, 0x80000000, v127
	v_xor_b32_e32 v105, 0x80000000, v129
	v_cndmask_b32_e64 v129, v129, v105, s[4:5]
	v_cndmask_b32_e64 v128, v128, v103, s[4:5]
	v_cndmask_b32_e64 v127, v127, v101, s[4:5]
	v_cndmask_b32_e64 v126, v126, v2, s[4:5]
	v_mov_b32_e32 v105, v106
	v_mov_b32_e32 v101, v102
	v_lshlrev_b64 v[102:103], 11, v[116:117]
	v_pk_fma_f32 v[104:105], v[104:105], v[124:125], v[126:127]
	v_lshl_add_u64 v[102:103], s[8:9], 0, v[102:103]
	v_pk_fma_f32 v[100:101], v[100:101], v[122:123], v[128:129]
	v_lshl_add_u64 v[102:103], s[24:25], 1, v[102:103]
	v_lshlrev_b32_e32 v2, 1, v152
	v_pk_mul_f32 v[104:105], v[104:105], s[30:31] op_sel_hi:[1,0]
	v_lshl_add_u64 v[102:103], v[102:103], 0, v[2:3]
	v_pk_mul_f32 v[100:101], v[100:101], s[30:31] op_sel_hi:[1,0]
	v_cvt_pk_bf16_f32 v104, v104, v105
	s_nop 0
	v_cvt_pk_bf16_f32 v105, v100, v101
	global_store_dwordx2 v[102:103], v[104:105], off
	v_pk_mul_f32 v[104:105], v[118:119], s[30:31] op_sel_hi:[1,0]
	v_pk_mul_f32 v[100:101], v[120:121], s[30:31] op_sel_hi:[1,0]
	v_cvt_pk_bf16_f32 v104, v104, v105
	s_nop 0
	v_cvt_pk_bf16_f32 v105, v100, v101
	global_store_dwordx2 v[102:103], v[104:105], off offset:32
	v_pk_mul_f32 v[104:105], v[112:113], s[30:31] op_sel_hi:[1,0]
	v_pk_mul_f32 v[100:101], v[114:115], s[30:31] op_sel_hi:[1,0]
	v_cvt_pk_bf16_f32 v104, v104, v105
	s_nop 0
	v_cvt_pk_bf16_f32 v105, v100, v101
	global_store_dwordx2 v[102:103], v[104:105], off offset:64
	v_pk_mul_f32 v[104:105], v[108:109], s[30:31] op_sel_hi:[1,0]
	v_pk_mul_f32 v[100:101], v[110:111], s[30:31] op_sel_hi:[1,0]
	v_cvt_pk_bf16_f32 v104, v104, v105
	s_nop 0
	v_cvt_pk_bf16_f32 v105, v100, v101
	global_store_dwordx2 v[102:103], v[104:105], off offset:96

.LBB0_472:
	s_andn2_b64 vcc, exec, s[30:31]
	s_cbranch_vccnz .LBB0_474
	v_pk_mul_f32 v[102:103], v[98:99], v[98:99]
	v_pk_mul_f32 v[104:105], v[96:97], v[96:97]
	s_movk_i32 s11, 0x4000
	v_pk_mov_b32 v[106:107], v[104:105], v[102:103] op_sel:[1,0]
	v_mov_b32_e32 v105, v103
	v_pk_add_f32 v[102:103], v[106:107], v[104:105]
	v_pk_mul_f32 v[104:105], v[94:95], v[94:95]
	v_pk_mul_f32 v[106:107], v[92:93], v[92:93]
	v_lshlrev_b32_e32 v2, 4, v100
	v_pk_mov_b32 v[108:109], v[106:107], v[104:105] op_sel:[1,0]
	v_mov_b32_e32 v107, v105
	v_cmp_gt_i32_e32 vcc, s11, v100
	v_and_b32_e32 v2, 0x1fff0, v2
	v_pk_add_f32 v[104:105], v[108:109], v[106:107]
	v_cndmask_b32_e32 v101, v230, v2, vcc
	v_mul_f32_e32 v2, v84, v84
	v_mul_f32_e32 v106, v85, v85
	v_pk_add_f32 v[102:103], v[102:103], v[102:103] op_sel:[0,1] op_sel_hi:[1,0]
	v_pk_add_f32 v[104:105], v[104:105], v[104:105] op_sel:[0,1] op_sel_hi:[1,0]
	v_mov_b32_e32 v103, v2
	v_mov_b32_e32 v105, v106
	v_mul_f32_e32 v2, v89, v89
	v_mul_f32_e32 v107, v86, v86
	v_pk_add_f32 v[102:103], v[102:103], v[104:105]
	v_pk_fma_f32 v[104:105], v[88:89], v[88:89], v[2:3] op_sel_hi:[1,1,0]
	v_mul_f32_e32 v2, v91, v91
	v_mul_f32_e32 v108, v87, v87
	v_mov_b32_e32 v105, v107
	v_pk_fma_f32 v[106:107], v[90:91], v[90:91], v[2:3] op_sel_hi:[1,1,0]
	s_mov_b32 s11, 0x800000
	v_mov_b32_e32 v107, v108
	v_pk_add_f32 v[104:105], v[104:105], v[106:107]
	s_mov_b32 s30, 0x3e38aa3b
	v_pk_add_f32 v[102:103], v[102:103], v[104:105]
	s_nop 0
	v_add_f32_e32 v2, v102, v103
	v_and_b32_e32 v103, 64, v229
	v_xor_b32_e32 v102, 16, v229
	v_add_u32_e32 v103, 64, v103
	v_cmp_lt_i32_e32 vcc, v102, v103
	s_nop 1
	v_cndmask_b32_e32 v102, v229, v102, vcc
	v_lshlrev_b32_e32 v102, 2, v102
	ds_bpermute_b32 v102, v102, v2
	s_waitcnt lgkmcnt(0)
	v_add_f32_e32 v2, v2, v102
	v_xor_b32_e32 v102, 32, v229
	v_cmp_lt_i32_e32 vcc, v102, v103
	s_nop 1
	v_cndmask_b32_e32 v102, v229, v102, vcc
	v_lshlrev_b32_e32 v113, 2, v102
	ds_bpermute_b32 v102, v113, v2
	s_waitcnt lgkmcnt(0)
	v_add_f32_e32 v2, v2, v102
	v_fmamk_f32 v2, v2, 0x3c800000, v226
	v_cmp_gt_f32_e32 vcc, s11, v2
	v_mul_f32_e32 v102, 0x4b800000, v2
	s_nop 0
	v_cndmask_b32_e32 v2, v2, v102, vcc
	v_rsq_f32_e32 v2, v2
	s_nop 0
	v_mul_f32_e32 v102, 0x45800000, v2
	v_cndmask_b32_e32 v2, v2, v102, vcc
	v_pk_mul_f32 v[96:97], v[96:97], v[2:3] op_sel_hi:[1,0]
	v_pk_mul_f32 v[98:99], v[98:99], v[2:3] op_sel_hi:[1,0]
	v_pk_mul_f32 v[94:95], v[94:95], v[2:3] op_sel_hi:[1,0]
	v_pk_mul_f32 v[92:93], v[92:93], v[2:3] op_sel_hi:[1,0]
	v_pk_mul_f32 v[90:91], v[90:91], v[2:3] op_sel_hi:[1,0]
	v_pk_mul_f32 v[88:89], v[88:89], v[2:3] op_sel_hi:[1,0]
	v_pk_mul_f32 v[86:87], v[86:87], v[2:3] op_sel_hi:[1,0]
	v_pk_mul_f32 v[84:85], v[84:85], v[2:3] op_sel_hi:[1,0]
	v_lshlrev_b32_e32 v2, 2, v101
	v_pk_mul_f32 v[108:109], v[32:33], v[96:97]
	v_pk_mul_f32 v[96:97], v[24:25], v[88:89]
	v_lshl_add_u64 v[88:89], v[154:155], 0, v[2:3]
	v_pk_mul_f32 v[106:107], v[34:35], v[98:99]
	v_pk_mul_f32 v[102:103], v[28:29], v[92:93]
	v_pk_mul_f32 v[104:105], v[30:31], v[94:95]
	v_pk_mul_f32 v[98:99], v[26:27], v[90:91]
	v_pk_mul_f32 v[92:93], v[20:21], v[84:85]
	v_pk_mul_f32 v[94:95], v[22:23], v[86:87]
	global_load_dwordx4 v[84:87], v[88:89], off offset:16
	s_nop 0
	global_load_dwordx4 v[88:91], v[88:89], off
	ds_bpermute_b32 v110, v113, v108
	ds_bpermute_b32 v111, v113, v109
	ds_bpermute_b32 v112, v113, v106
	ds_bpermute_b32 v113, v113, v107
	v_ashrrev_i32_e32 v101, 31, v100
	s_waitcnt vmcnt(1)
	v_mov_b32_e32 v114, v85
	v_mov_b32_e32 v115, v87
	s_waitcnt lgkmcnt(0)
	v_pk_mul_f32 v[112:113], v[114:115], v[112:113]
	s_waitcnt vmcnt(0)
	v_mov_b32_e32 v114, v89
	v_mov_b32_e32 v115, v91
	v_pk_mul_f32 v[110:111], v[114:115], v[110:111]
	v_xor_b32_e32 v87, 0x80000000, v112
	v_xor_b32_e32 v2, 0x80000000, v110
	v_xor_b32_e32 v85, 0x80000000, v111
	v_xor_b32_e32 v89, 0x80000000, v113
	v_cndmask_b32_e64 v113, v113, v89, s[4:5]
	v_cndmask_b32_e64 v112, v112, v87, s[4:5]
	v_cndmask_b32_e64 v111, v111, v85, s[4:5]
	v_cndmask_b32_e64 v110, v110, v2, s[4:5]
	v_mov_b32_e32 v89, v90
	v_mov_b32_e32 v85, v86
	v_lshlrev_b64 v[86:87], 11, v[100:101]
	v_pk_fma_f32 v[88:89], v[88:89], v[108:109], v[110:111]
	v_lshl_add_u64 v[86:87], s[8:9], 0, v[86:87]
	v_pk_fma_f32 v[84:85], v[84:85], v[106:107], v[112:113]
	v_lshl_add_u64 v[86:87], s[24:25], 1, v[86:87]
	v_lshlrev_b32_e32 v2, 1, v152
	v_pk_mul_f32 v[88:89], v[88:89], s[30:31] op_sel_hi:[1,0]
	v_lshl_add_u64 v[86:87], v[86:87], 0, v[2:3]
	v_pk_mul_f32 v[84:85], v[84:85], s[30:31] op_sel_hi:[1,0]
	v_cvt_pk_bf16_f32 v88, v88, v89
	s_nop 0
	v_cvt_pk_bf16_f32 v89, v84, v85
	global_store_dwordx2 v[86:87], v[88:89], off
	v_pk_mul_f32 v[88:89], v[102:103], s[30:31] op_sel_hi:[1,0]
	v_pk_mul_f32 v[84:85], v[104:105], s[30:31] op_sel_hi:[1,0]
	v_cvt_pk_bf16_f32 v88, v88, v89
	s_nop 0
	v_cvt_pk_bf16_f32 v89, v84, v85
	global_store_dwordx2 v[86:87], v[88:89], off offset:32
	v_pk_mul_f32 v[88:89], v[96:97], s[30:31] op_sel_hi:[1,0]
	v_pk_mul_f32 v[84:85], v[98:99], s[30:31] op_sel_hi:[1,0]
	v_cvt_pk_bf16_f32 v88, v88, v89
	s_nop 0
	v_cvt_pk_bf16_f32 v89, v84, v85
	global_store_dwordx2 v[86:87], v[88:89], off offset:64
	v_pk_mul_f32 v[88:89], v[92:93], s[30:31] op_sel_hi:[1,0]
	v_pk_mul_f32 v[84:85], v[94:95], s[30:31] op_sel_hi:[1,0]
	v_cvt_pk_bf16_f32 v88, v88, v89
	s_nop 0
	v_cvt_pk_bf16_f32 v89, v84, v85
	global_store_dwordx2 v[86:87], v[88:89], off offset:96

.LBB0_480:
	s_andn2_b64 vcc, exec, s[30:31]
	s_cbranch_vccnz .LBB0_482
	v_pk_mul_f32 v[86:87], v[82:83], v[82:83]
	v_pk_mul_f32 v[88:89], v[80:81], v[80:81]
	s_movk_i32 s11, 0x4000
	v_pk_mov_b32 v[90:91], v[88:89], v[86:87] op_sel:[1,0]
	v_mov_b32_e32 v89, v87
	v_pk_add_f32 v[86:87], v[90:91], v[88:89]
	v_pk_mul_f32 v[88:89], v[78:79], v[78:79]
	v_pk_mul_f32 v[90:91], v[76:77], v[76:77]
	v_lshlrev_b32_e32 v2, 4, v84
	v_pk_mov_b32 v[92:93], v[90:91], v[88:89] op_sel:[1,0]
	v_mov_b32_e32 v91, v89
	v_cmp_gt_i32_e32 vcc, s11, v84
	v_and_b32_e32 v2, 0x1fcf0, v2
	v_pk_add_f32 v[88:89], v[92:93], v[90:91]
	v_cndmask_b32_e32 v85, v230, v2, vcc
	v_mul_f32_e32 v2, v68, v68
	v_mul_f32_e32 v90, v69, v69
	v_pk_add_f32 v[86:87], v[86:87], v[86:87] op_sel:[0,1] op_sel_hi:[1,0]
	v_pk_add_f32 v[88:89], v[88:89], v[88:89] op_sel:[0,1] op_sel_hi:[1,0]
	v_mov_b32_e32 v87, v2
	v_mov_b32_e32 v89, v90
	v_mul_f32_e32 v2, v73, v73
	v_mul_f32_e32 v91, v70, v70
	v_pk_add_f32 v[86:87], v[86:87], v[88:89]
	v_pk_fma_f32 v[88:89], v[72:73], v[72:73], v[2:3] op_sel_hi:[1,1,0]
	v_mul_f32_e32 v2, v75, v75
	v_mul_f32_e32 v92, v71, v71
	v_mov_b32_e32 v89, v91
	v_pk_fma_f32 v[90:91], v[74:75], v[74:75], v[2:3] op_sel_hi:[1,1,0]
	s_mov_b32 s11, 0x800000
	v_mov_b32_e32 v91, v92
	v_pk_add_f32 v[88:89], v[88:89], v[90:91]
	s_mov_b32 s30, 0x3e38aa3b
	v_pk_add_f32 v[86:87], v[86:87], v[88:89]
	s_nop 0
	v_add_f32_e32 v2, v86, v87
	v_and_b32_e32 v87, 64, v229
	v_xor_b32_e32 v86, 16, v229
	v_add_u32_e32 v87, 64, v87
	v_cmp_lt_i32_e32 vcc, v86, v87
	s_nop 1
	v_cndmask_b32_e32 v86, v229, v86, vcc
	v_lshlrev_b32_e32 v86, 2, v86
	ds_bpermute_b32 v86, v86, v2
	s_waitcnt lgkmcnt(0)
	v_add_f32_e32 v2, v2, v86
	v_xor_b32_e32 v86, 32, v229
	v_cmp_lt_i32_e32 vcc, v86, v87
	s_nop 1
	v_cndmask_b32_e32 v86, v229, v86, vcc
	v_lshlrev_b32_e32 v97, 2, v86
	ds_bpermute_b32 v86, v97, v2
	s_waitcnt lgkmcnt(0)
	v_add_f32_e32 v2, v2, v86
	v_fmamk_f32 v2, v2, 0x3c800000, v226
	v_cmp_gt_f32_e32 vcc, s11, v2
	v_mul_f32_e32 v86, 0x4b800000, v2
	s_nop 0
	v_cndmask_b32_e32 v2, v2, v86, vcc
	v_rsq_f32_e32 v2, v2
	s_nop 0
	v_mul_f32_e32 v86, 0x45800000, v2
	v_cndmask_b32_e32 v2, v2, v86, vcc
	v_pk_mul_f32 v[80:81], v[80:81], v[2:3] op_sel_hi:[1,0]
	v_pk_mul_f32 v[82:83], v[82:83], v[2:3] op_sel_hi:[1,0]
	v_pk_mul_f32 v[78:79], v[78:79], v[2:3] op_sel_hi:[1,0]
	v_pk_mul_f32 v[76:77], v[76:77], v[2:3] op_sel_hi:[1,0]
	v_pk_mul_f32 v[74:75], v[74:75], v[2:3] op_sel_hi:[1,0]
	v_pk_mul_f32 v[72:73], v[72:73], v[2:3] op_sel_hi:[1,0]
	v_pk_mul_f32 v[70:71], v[70:71], v[2:3] op_sel_hi:[1,0]
	v_pk_mul_f32 v[68:69], v[68:69], v[2:3] op_sel_hi:[1,0]
	v_lshlrev_b32_e32 v2, 2, v85
	v_pk_mul_f32 v[92:93], v[32:33], v[80:81]
	v_pk_mul_f32 v[80:81], v[24:25], v[72:73]
	v_lshl_add_u64 v[72:73], v[154:155], 0, v[2:3]
	v_pk_mul_f32 v[90:91], v[34:35], v[82:83]
	v_pk_mul_f32 v[86:87], v[28:29], v[76:77]
	v_pk_mul_f32 v[88:89], v[30:31], v[78:79]
	v_pk_mul_f32 v[82:83], v[26:27], v[74:75]
	v_pk_mul_f32 v[76:77], v[20:21], v[68:69]
	v_pk_mul_f32 v[78:79], v[22:23], v[70:71]
	global_load_dwordx4 v[68:71], v[72:73], off offset:16
	s_nop 0
	global_load_dwordx4 v[72:75], v[72:73], off
	ds_bpermute_b32 v94, v97, v92
	ds_bpermute_b32 v95, v97, v93
	ds_bpermute_b32 v96, v97, v90
	ds_bpermute_b32 v97, v97, v91
	v_ashrrev_i32_e32 v85, 31, v84
	s_waitcnt vmcnt(1)
	v_mov_b32_e32 v98, v69
	v_mov_b32_e32 v99, v71
	s_waitcnt lgkmcnt(0)
	v_pk_mul_f32 v[96:97], v[98:99], v[96:97]
	s_waitcnt vmcnt(0)
	v_mov_b32_e32 v98, v73
	v_mov_b32_e32 v99, v75
	v_pk_mul_f32 v[94:95], v[98:99], v[94:95]
	v_xor_b32_e32 v71, 0x80000000, v96
	v_xor_b32_e32 v2, 0x80000000, v94
	v_xor_b32_e32 v69, 0x80000000, v95
	v_xor_b32_e32 v73, 0x80000000, v97
	v_cndmask_b32_e64 v97, v97, v73, s[4:5]
	v_cndmask_b32_e64 v96, v96, v71, s[4:5]
	v_cndmask_b32_e64 v95, v95, v69, s[4:5]
	v_cndmask_b32_e64 v94, v94, v2, s[4:5]
	v_mov_b32_e32 v73, v74
	v_mov_b32_e32 v69, v70
	v_lshlrev_b64 v[70:71], 11, v[84:85]
	v_pk_fma_f32 v[72:73], v[72:73], v[92:93], v[94:95]
	v_lshl_add_u64 v[70:71], s[8:9], 0, v[70:71]
	v_pk_fma_f32 v[68:69], v[68:69], v[90:91], v[96:97]
	v_lshl_add_u64 v[70:71], s[24:25], 1, v[70:71]
	v_lshlrev_b32_e32 v2, 1, v152
	v_pk_mul_f32 v[72:73], v[72:73], s[30:31] op_sel_hi:[1,0]
	v_lshl_add_u64 v[70:71], v[70:71], 0, v[2:3]
	v_pk_mul_f32 v[68:69], v[68:69], s[30:31] op_sel_hi:[1,0]
	v_cvt_pk_bf16_f32 v72, v72, v73
	s_nop 0
	v_cvt_pk_bf16_f32 v73, v68, v69
	global_store_dwordx2 v[70:71], v[72:73], off
	v_pk_mul_f32 v[72:73], v[86:87], s[30:31] op_sel_hi:[1,0]
	v_pk_mul_f32 v[68:69], v[88:89], s[30:31] op_sel_hi:[1,0]
	v_cvt_pk_bf16_f32 v72, v72, v73
	s_nop 0
	v_cvt_pk_bf16_f32 v73, v68, v69
	global_store_dwordx2 v[70:71], v[72:73], off offset:32
	v_pk_mul_f32 v[72:73], v[80:81], s[30:31] op_sel_hi:[1,0]
	v_pk_mul_f32 v[68:69], v[82:83], s[30:31] op_sel_hi:[1,0]
	v_cvt_pk_bf16_f32 v72, v72, v73
	s_nop 0
	v_cvt_pk_bf16_f32 v73, v68, v69
	global_store_dwordx2 v[70:71], v[72:73], off offset:64
	v_pk_mul_f32 v[72:73], v[76:77], s[30:31] op_sel_hi:[1,0]
	v_pk_mul_f32 v[68:69], v[78:79], s[30:31] op_sel_hi:[1,0]
	v_cvt_pk_bf16_f32 v72, v72, v73
	s_nop 0
	v_cvt_pk_bf16_f32 v73, v68, v69
	global_store_dwordx2 v[70:71], v[72:73], off offset:96

.LBB0_488:
	s_andn2_b64 vcc, exec, s[30:31]
	s_cbranch_vccnz .LBB0_490
	v_pk_mul_f32 v[70:71], v[66:67], v[66:67]
	v_pk_mul_f32 v[72:73], v[64:65], v[64:65]
	s_movk_i32 s11, 0x4000
	v_pk_mov_b32 v[74:75], v[72:73], v[70:71] op_sel:[1,0]
	v_mov_b32_e32 v73, v71
	v_pk_add_f32 v[70:71], v[74:75], v[72:73]
	v_pk_mul_f32 v[72:73], v[62:63], v[62:63]
	v_pk_mul_f32 v[74:75], v[60:61], v[60:61]
	v_lshlrev_b32_e32 v2, 4, v68
	v_pk_mov_b32 v[76:77], v[74:75], v[72:73] op_sel:[1,0]
	v_mov_b32_e32 v75, v73
	v_cmp_gt_i32_e32 vcc, s11, v68
	v_and_b32_e32 v2, 0x1fdf0, v2
	v_pk_add_f32 v[72:73], v[76:77], v[74:75]
	v_cndmask_b32_e32 v69, v230, v2, vcc
	v_mul_f32_e32 v2, v52, v52
	v_mul_f32_e32 v74, v53, v53
	v_pk_add_f32 v[70:71], v[70:71], v[70:71] op_sel:[0,1] op_sel_hi:[1,0]
	v_pk_add_f32 v[72:73], v[72:73], v[72:73] op_sel:[0,1] op_sel_hi:[1,0]
	v_mov_b32_e32 v71, v2
	v_mov_b32_e32 v73, v74
	v_mul_f32_e32 v2, v57, v57
	v_mul_f32_e32 v75, v54, v54
	v_pk_add_f32 v[70:71], v[70:71], v[72:73]
	v_pk_fma_f32 v[72:73], v[56:57], v[56:57], v[2:3] op_sel_hi:[1,1,0]
	v_mul_f32_e32 v2, v59, v59
	v_mul_f32_e32 v76, v55, v55
	v_mov_b32_e32 v73, v75
	v_pk_fma_f32 v[74:75], v[58:59], v[58:59], v[2:3] op_sel_hi:[1,1,0]
	s_mov_b32 s11, 0x800000
	v_mov_b32_e32 v75, v76
	v_pk_add_f32 v[72:73], v[72:73], v[74:75]
	s_mov_b32 s30, 0x3e38aa3b
	v_pk_add_f32 v[70:71], v[70:71], v[72:73]
	s_nop 0
	v_add_f32_e32 v2, v70, v71
	v_and_b32_e32 v71, 64, v229
	v_xor_b32_e32 v70, 16, v229
	v_add_u32_e32 v71, 64, v71
	v_cmp_lt_i32_e32 vcc, v70, v71
	s_nop 1
	v_cndmask_b32_e32 v70, v229, v70, vcc
	v_lshlrev_b32_e32 v70, 2, v70
	ds_bpermute_b32 v70, v70, v2
	s_waitcnt lgkmcnt(0)
	v_add_f32_e32 v2, v2, v70
	v_xor_b32_e32 v70, 32, v229
	v_cmp_lt_i32_e32 vcc, v70, v71
	s_nop 1
	v_cndmask_b32_e32 v70, v229, v70, vcc
	v_lshlrev_b32_e32 v81, 2, v70
	ds_bpermute_b32 v70, v81, v2
	s_waitcnt lgkmcnt(0)
	v_add_f32_e32 v2, v2, v70
	v_fmamk_f32 v2, v2, 0x3c800000, v226
	v_cmp_gt_f32_e32 vcc, s11, v2
	v_mul_f32_e32 v70, 0x4b800000, v2
	s_nop 0
	v_cndmask_b32_e32 v2, v2, v70, vcc
	v_rsq_f32_e32 v2, v2
	s_nop 0
	v_mul_f32_e32 v70, 0x45800000, v2
	v_cndmask_b32_e32 v2, v2, v70, vcc
	v_pk_mul_f32 v[64:65], v[64:65], v[2:3] op_sel_hi:[1,0]
	v_pk_mul_f32 v[66:67], v[66:67], v[2:3] op_sel_hi:[1,0]
	v_pk_mul_f32 v[62:63], v[62:63], v[2:3] op_sel_hi:[1,0]
	v_pk_mul_f32 v[60:61], v[60:61], v[2:3] op_sel_hi:[1,0]
	v_pk_mul_f32 v[58:59], v[58:59], v[2:3] op_sel_hi:[1,0]
	v_pk_mul_f32 v[56:57], v[56:57], v[2:3] op_sel_hi:[1,0]
	v_pk_mul_f32 v[54:55], v[54:55], v[2:3] op_sel_hi:[1,0]
	v_pk_mul_f32 v[52:53], v[52:53], v[2:3] op_sel_hi:[1,0]
	v_lshlrev_b32_e32 v2, 2, v69
	v_pk_mul_f32 v[76:77], v[32:33], v[64:65]
	v_pk_mul_f32 v[64:65], v[24:25], v[56:57]
	v_lshl_add_u64 v[56:57], v[154:155], 0, v[2:3]
	v_pk_mul_f32 v[74:75], v[34:35], v[66:67]
	v_pk_mul_f32 v[70:71], v[28:29], v[60:61]
	v_pk_mul_f32 v[72:73], v[30:31], v[62:63]
	v_pk_mul_f32 v[66:67], v[26:27], v[58:59]
	v_pk_mul_f32 v[60:61], v[20:21], v[52:53]
	v_pk_mul_f32 v[62:63], v[22:23], v[54:55]
	global_load_dwordx4 v[52:55], v[56:57], off offset:16
	s_nop 0
	global_load_dwordx4 v[56:59], v[56:57], off
	ds_bpermute_b32 v78, v81, v76
	ds_bpermute_b32 v79, v81, v77
	ds_bpermute_b32 v80, v81, v74
	ds_bpermute_b32 v81, v81, v75
	v_ashrrev_i32_e32 v69, 31, v68
	s_waitcnt vmcnt(1)
	v_mov_b32_e32 v82, v53
	v_mov_b32_e32 v83, v55
	s_waitcnt lgkmcnt(0)
	v_pk_mul_f32 v[80:81], v[82:83], v[80:81]
	s_waitcnt vmcnt(0)
	v_mov_b32_e32 v82, v57
	v_mov_b32_e32 v83, v59
	v_pk_mul_f32 v[78:79], v[82:83], v[78:79]
	v_xor_b32_e32 v55, 0x80000000, v80
	v_xor_b32_e32 v2, 0x80000000, v78
	v_xor_b32_e32 v53, 0x80000000, v79
	v_xor_b32_e32 v57, 0x80000000, v81
	v_cndmask_b32_e64 v81, v81, v57, s[4:5]
	v_cndmask_b32_e64 v80, v80, v55, s[4:5]
	v_cndmask_b32_e64 v79, v79, v53, s[4:5]
	v_cndmask_b32_e64 v78, v78, v2, s[4:5]
	v_mov_b32_e32 v57, v58
	v_mov_b32_e32 v53, v54
	v_lshlrev_b64 v[54:55], 11, v[68:69]
	v_pk_fma_f32 v[56:57], v[56:57], v[76:77], v[78:79]
	v_lshl_add_u64 v[54:55], s[8:9], 0, v[54:55]
	v_pk_fma_f32 v[52:53], v[52:53], v[74:75], v[80:81]
	v_lshl_add_u64 v[54:55], s[24:25], 1, v[54:55]
	v_lshlrev_b32_e32 v2, 1, v152
	v_pk_mul_f32 v[56:57], v[56:57], s[30:31] op_sel_hi:[1,0]
	v_lshl_add_u64 v[54:55], v[54:55], 0, v[2:3]
	v_pk_mul_f32 v[52:53], v[52:53], s[30:31] op_sel_hi:[1,0]
	v_cvt_pk_bf16_f32 v56, v56, v57
	s_nop 0
	v_cvt_pk_bf16_f32 v57, v52, v53
	global_store_dwordx2 v[54:55], v[56:57], off
	v_pk_mul_f32 v[56:57], v[70:71], s[30:31] op_sel_hi:[1,0]
	v_pk_mul_f32 v[52:53], v[72:73], s[30:31] op_sel_hi:[1,0]
	v_cvt_pk_bf16_f32 v56, v56, v57
	s_nop 0
	v_cvt_pk_bf16_f32 v57, v52, v53
	global_store_dwordx2 v[54:55], v[56:57], off offset:32
	v_pk_mul_f32 v[56:57], v[64:65], s[30:31] op_sel_hi:[1,0]
	v_pk_mul_f32 v[52:53], v[66:67], s[30:31] op_sel_hi:[1,0]
	v_cvt_pk_bf16_f32 v56, v56, v57
	s_nop 0
	v_cvt_pk_bf16_f32 v57, v52, v53
	global_store_dwordx2 v[54:55], v[56:57], off offset:64
	v_pk_mul_f32 v[56:57], v[60:61], s[30:31] op_sel_hi:[1,0]
	v_pk_mul_f32 v[52:53], v[62:63], s[30:31] op_sel_hi:[1,0]
	v_cvt_pk_bf16_f32 v56, v56, v57
	s_nop 0
	v_cvt_pk_bf16_f32 v57, v52, v53
	global_store_dwordx2 v[54:55], v[56:57], off offset:96

.LBB0_496:
	s_andn2_b64 vcc, exec, s[30:31]
	s_cbranch_vccnz .LBB0_498
	v_pk_mul_f32 v[54:55], v[50:51], v[50:51]
	v_pk_mul_f32 v[56:57], v[48:49], v[48:49]
	s_movk_i32 s11, 0x4000
	v_pk_mov_b32 v[58:59], v[56:57], v[54:55] op_sel:[1,0]
	v_mov_b32_e32 v57, v55
	v_pk_add_f32 v[54:55], v[58:59], v[56:57]
	v_pk_mul_f32 v[56:57], v[46:47], v[46:47]
	v_pk_mul_f32 v[58:59], v[44:45], v[44:45]
	v_lshlrev_b32_e32 v2, 4, v52
	v_pk_mov_b32 v[60:61], v[58:59], v[56:57] op_sel:[1,0]
	v_mov_b32_e32 v59, v57
	v_cmp_gt_i32_e32 vcc, s11, v52
	v_and_b32_e32 v2, 0x1fef0, v2
	v_pk_add_f32 v[56:57], v[60:61], v[58:59]
	v_cndmask_b32_e32 v53, v230, v2, vcc
	v_mul_f32_e32 v2, v36, v36
	v_mul_f32_e32 v58, v37, v37
	v_pk_add_f32 v[54:55], v[54:55], v[54:55] op_sel:[0,1] op_sel_hi:[1,0]
	v_pk_add_f32 v[56:57], v[56:57], v[56:57] op_sel:[0,1] op_sel_hi:[1,0]
	v_mov_b32_e32 v55, v2
	v_mov_b32_e32 v57, v58
	v_mul_f32_e32 v2, v41, v41
	v_mul_f32_e32 v59, v38, v38
	v_pk_add_f32 v[54:55], v[54:55], v[56:57]
	v_pk_fma_f32 v[56:57], v[40:41], v[40:41], v[2:3] op_sel_hi:[1,1,0]
	v_mul_f32_e32 v2, v43, v43
	v_mul_f32_e32 v60, v39, v39
	v_mov_b32_e32 v57, v59
	v_pk_fma_f32 v[58:59], v[42:43], v[42:43], v[2:3] op_sel_hi:[1,1,0]
	s_mov_b32 s11, 0x800000
	v_mov_b32_e32 v59, v60
	v_pk_add_f32 v[56:57], v[56:57], v[58:59]
	s_mov_b32 s30, 0x3e38aa3b
	v_pk_add_f32 v[54:55], v[54:55], v[56:57]
	s_nop 0
	v_add_f32_e32 v2, v54, v55
	v_and_b32_e32 v55, 64, v229
	v_xor_b32_e32 v54, 16, v229
	v_add_u32_e32 v55, 64, v55
	v_cmp_lt_i32_e32 vcc, v54, v55
	s_nop 1
	v_cndmask_b32_e32 v54, v229, v54, vcc
	v_lshlrev_b32_e32 v54, 2, v54
	ds_bpermute_b32 v54, v54, v2
	s_waitcnt lgkmcnt(0)
	v_add_f32_e32 v2, v2, v54
	v_xor_b32_e32 v54, 32, v229
	v_cmp_lt_i32_e32 vcc, v54, v55
	s_nop 1
	v_cndmask_b32_e32 v54, v229, v54, vcc
	v_lshlrev_b32_e32 v65, 2, v54
	ds_bpermute_b32 v54, v65, v2
	s_waitcnt lgkmcnt(0)
	v_add_f32_e32 v2, v2, v54
	v_fmamk_f32 v2, v2, 0x3c800000, v226
	v_cmp_gt_f32_e32 vcc, s11, v2
	v_mul_f32_e32 v54, 0x4b800000, v2
	s_nop 0
	v_cndmask_b32_e32 v2, v2, v54, vcc
	v_rsq_f32_e32 v2, v2
	s_nop 0
	v_mul_f32_e32 v54, 0x45800000, v2
	v_cndmask_b32_e32 v2, v2, v54, vcc
	v_pk_mul_f32 v[48:49], v[48:49], v[2:3] op_sel_hi:[1,0]
	v_pk_mul_f32 v[50:51], v[50:51], v[2:3] op_sel_hi:[1,0]
	v_pk_mul_f32 v[46:47], v[46:47], v[2:3] op_sel_hi:[1,0]
	v_pk_mul_f32 v[44:45], v[44:45], v[2:3] op_sel_hi:[1,0]
	v_pk_mul_f32 v[42:43], v[42:43], v[2:3] op_sel_hi:[1,0]
	v_pk_mul_f32 v[40:41], v[40:41], v[2:3] op_sel_hi:[1,0]
	v_pk_mul_f32 v[38:39], v[38:39], v[2:3] op_sel_hi:[1,0]
	v_pk_mul_f32 v[36:37], v[36:37], v[2:3] op_sel_hi:[1,0]
	v_lshlrev_b32_e32 v2, 2, v53
	v_pk_mul_f32 v[60:61], v[32:33], v[48:49]
	v_pk_mul_f32 v[48:49], v[24:25], v[40:41]
	v_lshl_add_u64 v[40:41], v[154:155], 0, v[2:3]
	v_pk_mul_f32 v[58:59], v[34:35], v[50:51]
	v_pk_mul_f32 v[54:55], v[28:29], v[44:45]
	v_pk_mul_f32 v[56:57], v[30:31], v[46:47]
	v_pk_mul_f32 v[50:51], v[26:27], v[42:43]
	v_pk_mul_f32 v[44:45], v[20:21], v[36:37]
	v_pk_mul_f32 v[46:47], v[22:23], v[38:39]
	global_load_dwordx4 v[36:39], v[40:41], off offset:16
	s_nop 0
	global_load_dwordx4 v[40:43], v[40:41], off
	ds_bpermute_b32 v62, v65, v60
	ds_bpermute_b32 v63, v65, v61
	ds_bpermute_b32 v64, v65, v58
	ds_bpermute_b32 v65, v65, v59
	v_ashrrev_i32_e32 v53, 31, v52
	s_waitcnt vmcnt(1)
	v_mov_b32_e32 v66, v37
	v_mov_b32_e32 v67, v39
	s_waitcnt lgkmcnt(0)
	v_pk_mul_f32 v[64:65], v[66:67], v[64:65]
	s_waitcnt vmcnt(0)
	v_mov_b32_e32 v66, v41
	v_mov_b32_e32 v67, v43
	v_pk_mul_f32 v[62:63], v[66:67], v[62:63]
	v_xor_b32_e32 v39, 0x80000000, v64
	v_xor_b32_e32 v2, 0x80000000, v62
	v_xor_b32_e32 v37, 0x80000000, v63
	v_xor_b32_e32 v41, 0x80000000, v65
	v_cndmask_b32_e64 v65, v65, v41, s[4:5]
	v_cndmask_b32_e64 v64, v64, v39, s[4:5]
	v_cndmask_b32_e64 v63, v63, v37, s[4:5]
	v_cndmask_b32_e64 v62, v62, v2, s[4:5]
	v_mov_b32_e32 v41, v42
	v_mov_b32_e32 v37, v38
	v_lshlrev_b64 v[38:39], 11, v[52:53]
	v_pk_fma_f32 v[40:41], v[40:41], v[60:61], v[62:63]
	v_lshl_add_u64 v[38:39], s[8:9], 0, v[38:39]
	v_pk_fma_f32 v[36:37], v[36:37], v[58:59], v[64:65]
	v_lshl_add_u64 v[38:39], s[24:25], 1, v[38:39]
	v_lshlrev_b32_e32 v2, 1, v152
	v_pk_mul_f32 v[40:41], v[40:41], s[30:31] op_sel_hi:[1,0]
	v_lshl_add_u64 v[38:39], v[38:39], 0, v[2:3]
	v_pk_mul_f32 v[36:37], v[36:37], s[30:31] op_sel_hi:[1,0]
	v_cvt_pk_bf16_f32 v40, v40, v41
	s_nop 0
	v_cvt_pk_bf16_f32 v41, v36, v37
	global_store_dwordx2 v[38:39], v[40:41], off
	v_pk_mul_f32 v[40:41], v[54:55], s[30:31] op_sel_hi:[1,0]
	v_pk_mul_f32 v[36:37], v[56:57], s[30:31] op_sel_hi:[1,0]
	v_cvt_pk_bf16_f32 v40, v40, v41
	s_nop 0
	v_cvt_pk_bf16_f32 v41, v36, v37
	global_store_dwordx2 v[38:39], v[40:41], off offset:32
	v_pk_mul_f32 v[40:41], v[48:49], s[30:31] op_sel_hi:[1,0]
	v_pk_mul_f32 v[36:37], v[50:51], s[30:31] op_sel_hi:[1,0]
	v_cvt_pk_bf16_f32 v40, v40, v41
	s_nop 0
	v_cvt_pk_bf16_f32 v41, v36, v37
	global_store_dwordx2 v[38:39], v[40:41], off offset:64
	v_pk_mul_f32 v[40:41], v[44:45], s[30:31] op_sel_hi:[1,0]
	v_pk_mul_f32 v[36:37], v[46:47], s[30:31] op_sel_hi:[1,0]
	v_cvt_pk_bf16_f32 v40, v40, v41
	s_nop 0
	v_cvt_pk_bf16_f32 v41, v36, v37
	global_store_dwordx2 v[38:39], v[40:41], off offset:96

.LBB0_504:
	s_andn2_b64 vcc, exec, s[26:27]
	s_cbranch_vccnz .LBB0_506
	v_pk_mul_f32 v[38:39], v[18:19], v[18:19]
	v_pk_mul_f32 v[40:41], v[16:17], v[16:17]
	s_movk_i32 s11, 0x4000
	v_pk_mov_b32 v[42:43], v[40:41], v[38:39] op_sel:[1,0]
	v_mov_b32_e32 v41, v39
	v_pk_add_f32 v[38:39], v[42:43], v[40:41]
	v_pk_mul_f32 v[40:41], v[14:15], v[14:15]
	v_pk_mul_f32 v[42:43], v[12:13], v[12:13]
	v_lshlrev_b32_e32 v2, 4, v36
	v_pk_mov_b32 v[44:45], v[42:43], v[40:41] op_sel:[1,0]
	v_mov_b32_e32 v43, v41
	v_cmp_gt_i32_e32 vcc, s11, v36
	v_and_b32_e32 v2, 0x1fff0, v2
	v_pk_add_f32 v[40:41], v[44:45], v[42:43]
	v_cndmask_b32_e32 v37, v230, v2, vcc
	v_mul_f32_e32 v2, v4, v4
	v_mul_f32_e32 v42, v5, v5
	v_pk_add_f32 v[38:39], v[38:39], v[38:39] op_sel:[0,1] op_sel_hi:[1,0]
	v_pk_add_f32 v[40:41], v[40:41], v[40:41] op_sel:[0,1] op_sel_hi:[1,0]
	v_mov_b32_e32 v39, v2
	v_mov_b32_e32 v41, v42
	v_mul_f32_e32 v2, v9, v9
	v_mul_f32_e32 v43, v6, v6
	v_pk_add_f32 v[38:39], v[38:39], v[40:41]
	v_pk_fma_f32 v[40:41], v[8:9], v[8:9], v[2:3] op_sel_hi:[1,1,0]
	v_mul_f32_e32 v2, v11, v11
	v_mul_f32_e32 v44, v7, v7
	v_mov_b32_e32 v41, v43
	v_pk_fma_f32 v[42:43], v[10:11], v[10:11], v[2:3] op_sel_hi:[1,1,0]
	s_mov_b32 s11, 0x800000
	v_mov_b32_e32 v43, v44
	v_pk_add_f32 v[40:41], v[40:41], v[42:43]
	s_nop 0
	v_pk_add_f32 v[38:39], v[38:39], v[40:41]
	s_nop 0
	v_add_f32_e32 v2, v38, v39
	v_and_b32_e32 v39, 64, v229
	v_xor_b32_e32 v38, 16, v229
	v_add_u32_e32 v39, 64, v39
	v_cmp_lt_i32_e32 vcc, v38, v39
	s_nop 1
	v_cndmask_b32_e32 v38, v229, v38, vcc
	v_lshlrev_b32_e32 v38, 2, v38
	ds_bpermute_b32 v38, v38, v2
	s_waitcnt lgkmcnt(0)
	v_add_f32_e32 v2, v2, v38
	v_xor_b32_e32 v38, 32, v229
	v_cmp_lt_i32_e32 vcc, v38, v39
	s_nop 1
	v_cndmask_b32_e32 v38, v229, v38, vcc
	v_lshlrev_b32_e32 v38, 2, v38
	ds_bpermute_b32 v39, v38, v2
	s_waitcnt lgkmcnt(0)
	v_add_f32_e32 v2, v2, v39
	v_fmamk_f32 v2, v2, 0x3c800000, v226
	v_cmp_gt_f32_e32 vcc, s11, v2
	v_mul_f32_e32 v39, 0x4b800000, v2
	s_nop 0
	v_cndmask_b32_e32 v2, v2, v39, vcc
	v_rsq_f32_e32 v2, v2
	s_nop 0
	v_mul_f32_e32 v39, 0x45800000, v2
	v_cndmask_b32_e32 v2, v2, v39, vcc
	v_pk_mul_f32 v[16:17], v[16:17], v[2:3] op_sel_hi:[1,0]
	v_pk_mul_f32 v[18:19], v[18:19], v[2:3] op_sel_hi:[1,0]
	v_pk_mul_f32 v[14:15], v[14:15], v[2:3] op_sel_hi:[1,0]
	v_pk_mul_f32 v[12:13], v[12:13], v[2:3] op_sel_hi:[1,0]
	v_pk_mul_f32 v[10:11], v[10:11], v[2:3] op_sel_hi:[1,0]
	v_pk_mul_f32 v[8:9], v[8:9], v[2:3] op_sel_hi:[1,0]
	v_pk_mul_f32 v[6:7], v[6:7], v[2:3] op_sel_hi:[1,0]
	v_pk_mul_f32 v[4:5], v[4:5], v[2:3] op_sel_hi:[1,0]
	v_lshlrev_b32_e32 v2, 2, v37
	v_pk_mul_f32 v[32:33], v[32:33], v[16:17]
	v_pk_mul_f32 v[16:17], v[24:25], v[8:9]
	v_lshl_add_u64 v[8:9], v[154:155], 0, v[2:3]
	v_pk_mul_f32 v[34:35], v[34:35], v[18:19]
	v_pk_mul_f32 v[28:29], v[28:29], v[12:13]
	v_pk_mul_f32 v[30:31], v[30:31], v[14:15]
	v_pk_mul_f32 v[18:19], v[26:27], v[10:11]
	v_pk_mul_f32 v[12:13], v[20:21], v[4:5]
	v_pk_mul_f32 v[14:15], v[22:23], v[6:7]
	global_load_dwordx4 v[4:7], v[8:9], off offset:16
	s_nop 0
	global_load_dwordx4 v[8:11], v[8:9], off
	ds_bpermute_b32 v22, v38, v34
	ds_bpermute_b32 v23, v38, v35
	ds_bpermute_b32 v20, v38, v32
	ds_bpermute_b32 v21, v38, v33
	v_ashrrev_i32_e32 v37, 31, v36
	s_waitcnt vmcnt(1)
	v_mov_b32_e32 v24, v5
	v_mov_b32_e32 v25, v7
	s_waitcnt lgkmcnt(2)
	v_pk_mul_f32 v[22:23], v[24:25], v[22:23]
	s_waitcnt vmcnt(0)
	v_mov_b32_e32 v24, v9
	v_mov_b32_e32 v25, v11
	s_waitcnt lgkmcnt(0)
	v_pk_mul_f32 v[20:21], v[24:25], v[20:21]
	v_xor_b32_e32 v7, 0x80000000, v22
	v_xor_b32_e32 v5, 0x80000000, v21
	v_xor_b32_e32 v2, 0x80000000, v20
	v_xor_b32_e32 v9, 0x80000000, v23
	v_cndmask_b32_e64 v22, v22, v7, s[4:5]
	v_cndmask_b32_e64 v21, v21, v5, s[4:5]
	v_mov_b32_e32 v5, v6
	v_lshlrev_b64 v[6:7], 11, v[36:37]
	v_cndmask_b32_e64 v23, v23, v9, s[4:5]
	v_cndmask_b32_e64 v20, v20, v2, s[4:5]
	v_mov_b32_e32 v9, v10
	v_lshl_add_u64 v[6:7], s[8:9], 0, v[6:7]
	v_pk_fma_f32 v[8:9], v[8:9], v[32:33], v[20:21]
	v_lshl_add_u64 v[6:7], s[24:25], 1, v[6:7]
	s_mov_b32 s24, 0x3e38aa3b
	v_pk_fma_f32 v[4:5], v[4:5], v[34:35], v[22:23]
	v_lshlrev_b32_e32 v2, 1, v152
	v_pk_mul_f32 v[8:9], v[8:9], s[24:25] op_sel_hi:[1,0]
	v_lshl_add_u64 v[6:7], v[6:7], 0, v[2:3]
	v_pk_mul_f32 v[4:5], v[4:5], s[24:25] op_sel_hi:[1,0]
	v_cvt_pk_bf16_f32 v8, v8, v9
	s_nop 0
	v_cvt_pk_bf16_f32 v9, v4, v5
	global_store_dwordx2 v[6:7], v[8:9], off
	v_pk_mul_f32 v[8:9], v[28:29], s[24:25] op_sel_hi:[1,0]
	v_pk_mul_f32 v[4:5], v[30:31], s[24:25] op_sel_hi:[1,0]
	v_cvt_pk_bf16_f32 v8, v8, v9
	s_nop 0
	v_cvt_pk_bf16_f32 v9, v4, v5
	global_store_dwordx2 v[6:7], v[8:9], off offset:32
	v_pk_mul_f32 v[8:9], v[16:17], s[24:25] op_sel_hi:[1,0]
	v_pk_mul_f32 v[4:5], v[18:19], s[24:25] op_sel_hi:[1,0]
	v_cvt_pk_bf16_f32 v8, v8, v9
	s_nop 0
	v_cvt_pk_bf16_f32 v9, v4, v5
	global_store_dwordx2 v[6:7], v[8:9], off offset:64
	v_pk_mul_f32 v[8:9], v[12:13], s[24:25] op_sel_hi:[1,0]
	v_pk_mul_f32 v[4:5], v[14:15], s[24:25] op_sel_hi:[1,0]
	v_cvt_pk_bf16_f32 v8, v8, v9
	s_nop 0
	v_cvt_pk_bf16_f32 v9, v4, v5
	global_store_dwordx2 v[6:7], v[8:9], off offset:96
